# GEMM tiles: first k-iteration peeled, each accumulator's first MFMA takes C=0, the 128-register clear before every tile is gone
# speedup vs baseline: 1.0056x; 1.0056x over previous
.LBB0_258:
	s_ashr_i32 s15, s14, 31
	s_lshl_b64 s[16:17], s[14:15], 19
	s_add_u32 s16, s28, s16
	s_addc_u32 s17, s29, s17
	s_and_b64 s[18:19], s[0:1], exec
	s_cselect_b32 s15, s17, s23
	s_cselect_b32 s47, s16, s22
	s_ashr_i32 s13, s12, 31
	s_lshl_b64 s[18:19], s[12:13], 19
	s_add_u32 s18, s30, s18
	s_addc_u32 s19, s31, s19
	s_and_b64 s[26:27], s[0:1], exec
	s_cselect_b32 s13, s19, s25
	s_cselect_b32 s48, s18, s24
	s_add_u32 s22, s22, 0x40080
	s_addc_u32 s23, s23, 0
	s_add_u32 s49, s24, 0x100
	s_addc_u32 s50, s25, 0
	s_mov_b32 s51, -2
	ds_read_b128 v[152:155], v149
	ds_read_b128 v[156:159], v149 offset:1024
	ds_read_b128 v[160:163], v149 offset:2048
	ds_read_b128 v[164:167], v149 offset:3072
	ds_read_b128 v[168:171], v150
	ds_read_b128 v[172:175], v150 offset:1024
	ds_read_b128 v[176:179], v150 offset:2048
	ds_read_b128 v[184:187], v150 offset:3072
	s_add_u32 s24, s22, 0xfffc0080
	s_addc_u32 s25, s23, -1
	s_cmp_eq_u32 s51, 12
	s_cselect_b32 s27, s15, s25
	s_cselect_b32 s26, s47, s24
	s_cselect_b32 s25, s13, s50
	s_cselect_b32 s24, s48, s49
	v_lshl_add_u64 v[144:145], s[22:23], 0, v[136:137]
	s_add_i32 m0, s21, 0xc000
	ds_read_b128 v[188:191], v151
	ds_read_b128 v[192:195], v151 offset:1024
	ds_read_b128 v[196:199], v151 offset:2048
	ds_read_b128 v[200:203], v151 offset:3072
	ds_read_b128 v[204:207], v151 offset:4096
	ds_read_b128 v[208:211], v151 offset:5120
	ds_read_b128 v[212:215], v151 offset:6144
	ds_read_b128 v[216:219], v151 offset:7168
	global_load_lds_dwordx4 v[144:145], off
	v_lshl_add_u64 v[144:145], s[22:23], 0, v[138:139]
	s_add_i32 m0, s21, 0xe000
	s_nop 0
	global_load_lds_dwordx4 v[144:145], off
	s_waitcnt vmcnt(8)
	s_waitcnt lgkmcnt(0)
	s_barrier
	s_setprio 1
	v_mfma_f32_16x16x32_bf16 v[124:127], v[152:155], v[188:191], 0
	v_mfma_f32_16x16x32_bf16 v[120:123], v[160:163], v[188:191], 0
	v_mfma_f32_16x16x32_bf16 v[108:111], v[152:155], v[196:199], 0
	v_mfma_f32_16x16x32_bf16 v[104:107], v[160:163], v[196:199], 0
	v_mfma_f32_16x16x32_bf16 v[92:95], v[152:155], v[204:207], 0
	v_mfma_f32_16x16x32_bf16 v[88:91], v[160:163], v[204:207], 0
	v_mfma_f32_16x16x32_bf16 v[76:79], v[152:155], v[212:215], 0
	v_mfma_f32_16x16x32_bf16 v[72:75], v[160:163], v[212:215], 0
	v_mfma_f32_16x16x32_bf16 v[124:127], v[156:159], v[192:195], v[124:127]
	v_mfma_f32_16x16x32_bf16 v[120:123], v[164:167], v[192:195], v[120:123]
	v_mfma_f32_16x16x32_bf16 v[108:111], v[156:159], v[200:203], v[108:111]
	v_mfma_f32_16x16x32_bf16 v[104:107], v[164:167], v[200:203], v[104:107]
	v_mfma_f32_16x16x32_bf16 v[92:95], v[156:159], v[208:211], v[92:95]
	v_mfma_f32_16x16x32_bf16 v[88:91], v[164:167], v[208:211], v[88:91]
	v_mfma_f32_16x16x32_bf16 v[76:79], v[156:159], v[216:219], v[76:79]
	v_mfma_f32_16x16x32_bf16 v[72:75], v[164:167], v[216:219], v[72:75]
	v_mfma_f32_16x16x32_bf16 v[116:119], v[168:171], v[188:191], 0
	v_mfma_f32_16x16x32_bf16 v[112:115], v[176:179], v[188:191], 0
	v_mfma_f32_16x16x32_bf16 v[100:103], v[168:171], v[196:199], 0
	v_mfma_f32_16x16x32_bf16 v[96:99], v[176:179], v[196:199], 0
	v_mfma_f32_16x16x32_bf16 v[84:87], v[168:171], v[204:207], 0
	v_mfma_f32_16x16x32_bf16 v[80:83], v[176:179], v[204:207], 0
	v_mfma_f32_16x16x32_bf16 v[68:71], v[168:171], v[212:215], 0
	v_mfma_f32_16x16x32_bf16 v[64:67], v[176:179], v[212:215], 0
	v_mfma_f32_16x16x32_bf16 v[116:119], v[172:175], v[192:195], v[116:119]
	v_mfma_f32_16x16x32_bf16 v[112:115], v[184:187], v[192:195], v[112:115]
	v_mfma_f32_16x16x32_bf16 v[100:103], v[172:175], v[200:203], v[100:103]
	v_mfma_f32_16x16x32_bf16 v[96:99], v[184:187], v[200:203], v[96:99]
	v_mfma_f32_16x16x32_bf16 v[84:87], v[172:175], v[208:211], v[84:87]
	v_mfma_f32_16x16x32_bf16 v[80:83], v[184:187], v[208:211], v[80:83]
	v_mfma_f32_16x16x32_bf16 v[68:71], v[172:175], v[216:219], v[68:71]
	v_mfma_f32_16x16x32_bf16 v[64:67], v[184:187], v[216:219], v[64:67]
	s_setprio 0
	s_barrier
	s_add_i32 s52, s43, s34
	v_lshl_add_u64 v[144:145], s[24:25], 0, v[130:131]
	s_mov_b32 m0, s52
	ds_read_b128 v[188:191], v151 offset:16384
	ds_read_b128 v[192:195], v151 offset:17408
	ds_read_b128 v[196:199], v151 offset:18432
	ds_read_b128 v[200:203], v151 offset:19456
	ds_read_b128 v[204:207], v151 offset:20480
	ds_read_b128 v[208:211], v151 offset:21504
	ds_read_b128 v[212:215], v151 offset:22528
	ds_read_b128 v[216:219], v151 offset:23552
	global_load_lds_dwordx4 v[144:145], off
	s_add_i32 m0, s52, 0x2000
	s_add_u32 s52, s24, 0x40000
	v_lshl_add_u64 v[180:181], s[24:25], 0, v[134:135]
	s_addc_u32 s53, s25, 0
	s_add_i32 s54, s44, s34
	global_load_lds_dwordx4 v[180:181], off
	v_lshl_add_u64 v[220:221], s[52:53], 0, v[130:131]
	s_mov_b32 m0, s54
	v_lshl_add_u64 v[222:223], s[26:27], 0, v[132:133]
	global_load_lds_dwordx4 v[220:221], off
	v_lshl_add_u64 v[220:221], s[52:53], 0, v[134:135]
	s_add_i32 m0, s54, 0x2000
	s_nop 0
	global_load_lds_dwordx4 v[220:221], off
	v_lshl_add_u64 v[220:221], s[26:27], 0, v[128:129]
	s_mov_b32 m0, s21
	s_nop 0
	global_load_lds_dwordx4 v[220:221], off
	s_mov_b32 m0, s36
	s_nop 0
	global_load_lds_dwordx4 v[222:223], off
	s_waitcnt vmcnt(8)
	s_waitcnt lgkmcnt(0)
	s_barrier
	s_setprio 1
	v_mfma_f32_16x16x32_bf16 v[60:63], v[152:155], v[188:191], 0
	v_mfma_f32_16x16x32_bf16 v[56:59], v[160:163], v[188:191], 0
	v_mfma_f32_16x16x32_bf16 v[44:47], v[152:155], v[196:199], 0
	v_mfma_f32_16x16x32_bf16 v[40:43], v[160:163], v[196:199], 0
	v_mfma_f32_16x16x32_bf16 v[28:31], v[152:155], v[204:207], 0
	v_mfma_f32_16x16x32_bf16 v[24:27], v[160:163], v[204:207], 0
	v_mfma_f32_16x16x32_bf16 v[12:15], v[152:155], v[212:215], 0
	v_mfma_f32_16x16x32_bf16 v[8:11], v[160:163], v[212:215], 0
	v_mfma_f32_16x16x32_bf16 v[60:63], v[156:159], v[192:195], v[60:63]
	v_mfma_f32_16x16x32_bf16 v[56:59], v[164:167], v[192:195], v[56:59]
	v_mfma_f32_16x16x32_bf16 v[44:47], v[156:159], v[200:203], v[44:47]
	v_mfma_f32_16x16x32_bf16 v[40:43], v[164:167], v[200:203], v[40:43]
	v_mfma_f32_16x16x32_bf16 v[28:31], v[156:159], v[208:211], v[28:31]
	v_mfma_f32_16x16x32_bf16 v[24:27], v[164:167], v[208:211], v[24:27]
	v_mfma_f32_16x16x32_bf16 v[12:15], v[156:159], v[216:219], v[12:15]
	v_mfma_f32_16x16x32_bf16 v[8:11], v[164:167], v[216:219], v[8:11]
	v_mfma_f32_16x16x32_bf16 v[52:55], v[168:171], v[188:191], 0
	v_mfma_f32_16x16x32_bf16 v[48:51], v[176:179], v[188:191], 0
	v_mfma_f32_16x16x32_bf16 v[36:39], v[168:171], v[196:199], 0
	v_mfma_f32_16x16x32_bf16 v[32:35], v[176:179], v[196:199], 0
	v_mfma_f32_16x16x32_bf16 v[20:23], v[168:171], v[204:207], 0
	v_mfma_f32_16x16x32_bf16 v[16:19], v[176:179], v[204:207], 0
	v_mfma_f32_16x16x32_bf16 v[4:7], v[168:171], v[212:215], 0
	v_mfma_f32_16x16x32_bf16 v[0:3], v[176:179], v[212:215], 0
	v_mfma_f32_16x16x32_bf16 v[52:55], v[172:175], v[192:195], v[52:55]
	v_mfma_f32_16x16x32_bf16 v[48:51], v[184:187], v[192:195], v[48:51]
	v_mfma_f32_16x16x32_bf16 v[36:39], v[172:175], v[200:203], v[36:39]
	v_mfma_f32_16x16x32_bf16 v[32:35], v[184:187], v[200:203], v[32:35]
	v_mfma_f32_16x16x32_bf16 v[20:23], v[172:175], v[208:211], v[20:23]
	v_mfma_f32_16x16x32_bf16 v[16:19], v[184:187], v[208:211], v[16:19]
	v_mfma_f32_16x16x32_bf16 v[4:7], v[172:175], v[216:219], v[4:7]
	v_mfma_f32_16x16x32_bf16 v[0:3], v[184:187], v[216:219], v[0:3]
	s_setprio 0
	s_barrier
	s_add_i32 s52, 0, 0x18000
	s_add_i32 s53, 0, 0x1c000
	v_add_u32_e32 v164, s52, v147
	v_add_u32_e32 v183, s53, v147
	ds_read_b128 v[152:155], v164
	ds_read_b128 v[156:159], v164 offset:1024
	ds_read_b128 v[160:163], v164 offset:2048
	ds_read_b128 v[164:167], v164 offset:3072
	ds_read_b128 v[168:171], v183
	ds_read_b128 v[172:175], v183 offset:1024
	ds_read_b128 v[176:179], v183 offset:2048
	ds_read_b128 v[184:187], v183 offset:3072
	s_add_u32 s26, s26, 0x40000
	s_addc_u32 s27, s27, 0
	s_mov_b32 m0, s37
	v_lshl_add_u64 v[224:225], s[26:27], 0, v[128:129]
	ds_read_b128 v[188:191], v151 offset:32768
	ds_read_b128 v[192:195], v151 offset:33792
	ds_read_b128 v[196:199], v151 offset:34816
	ds_read_b128 v[200:203], v151 offset:35840
	ds_read_b128 v[204:207], v151 offset:36864
	ds_read_b128 v[208:211], v151 offset:37888
	ds_read_b128 v[212:215], v151 offset:38912
	ds_read_b128 v[216:219], v151 offset:39936
	global_load_lds_dwordx4 v[224:225], off
	v_lshl_add_u64 v[224:225], s[26:27], 0, v[132:133]
	s_mov_b32 m0, s38
	s_nop 0
	global_load_lds_dwordx4 v[224:225], off
	s_waitcnt vmcnt(8)
	s_waitcnt lgkmcnt(0)
	s_barrier
	s_setprio 1
	v_mfma_f32_16x16x32_bf16 v[124:127], v[152:155], v[188:191], v[124:127]
	v_mfma_f32_16x16x32_bf16 v[120:123], v[160:163], v[188:191], v[120:123]
	v_mfma_f32_16x16x32_bf16 v[108:111], v[152:155], v[196:199], v[108:111]
	v_mfma_f32_16x16x32_bf16 v[104:107], v[160:163], v[196:199], v[104:107]
	v_mfma_f32_16x16x32_bf16 v[92:95], v[152:155], v[204:207], v[92:95]
	v_mfma_f32_16x16x32_bf16 v[88:91], v[160:163], v[204:207], v[88:91]
	v_mfma_f32_16x16x32_bf16 v[76:79], v[152:155], v[212:215], v[76:79]
	v_mfma_f32_16x16x32_bf16 v[72:75], v[160:163], v[212:215], v[72:75]
	v_mfma_f32_16x16x32_bf16 v[124:127], v[156:159], v[192:195], v[124:127]
	v_mfma_f32_16x16x32_bf16 v[120:123], v[164:167], v[192:195], v[120:123]
	v_mfma_f32_16x16x32_bf16 v[108:111], v[156:159], v[200:203], v[108:111]
	v_mfma_f32_16x16x32_bf16 v[104:107], v[164:167], v[200:203], v[104:107]
	v_mfma_f32_16x16x32_bf16 v[92:95], v[156:159], v[208:211], v[92:95]
	v_mfma_f32_16x16x32_bf16 v[88:91], v[164:167], v[208:211], v[88:91]
	v_mfma_f32_16x16x32_bf16 v[76:79], v[156:159], v[216:219], v[76:79]
	v_mfma_f32_16x16x32_bf16 v[72:75], v[164:167], v[216:219], v[72:75]
	v_mfma_f32_16x16x32_bf16 v[116:119], v[168:171], v[188:191], v[116:119]
	v_mfma_f32_16x16x32_bf16 v[112:115], v[176:179], v[188:191], v[112:115]
	v_mfma_f32_16x16x32_bf16 v[100:103], v[168:171], v[196:199], v[100:103]
	v_mfma_f32_16x16x32_bf16 v[96:99], v[176:179], v[196:199], v[96:99]
	v_mfma_f32_16x16x32_bf16 v[84:87], v[168:171], v[204:207], v[84:87]
	v_mfma_f32_16x16x32_bf16 v[80:83], v[176:179], v[204:207], v[80:83]
	v_mfma_f32_16x16x32_bf16 v[68:71], v[168:171], v[212:215], v[68:71]
	v_mfma_f32_16x16x32_bf16 v[64:67], v[176:179], v[212:215], v[64:67]
	v_mfma_f32_16x16x32_bf16 v[116:119], v[172:175], v[192:195], v[116:119]
	v_mfma_f32_16x16x32_bf16 v[112:115], v[184:187], v[192:195], v[112:115]
	v_mfma_f32_16x16x32_bf16 v[100:103], v[172:175], v[200:203], v[100:103]
	v_mfma_f32_16x16x32_bf16 v[96:99], v[184:187], v[200:203], v[96:99]
	v_mfma_f32_16x16x32_bf16 v[84:87], v[172:175], v[208:211], v[84:87]
	v_mfma_f32_16x16x32_bf16 v[80:83], v[184:187], v[208:211], v[80:83]
	v_mfma_f32_16x16x32_bf16 v[68:71], v[172:175], v[216:219], v[68:71]
	v_mfma_f32_16x16x32_bf16 v[64:67], v[184:187], v[216:219], v[64:67]
	s_setprio 0
	s_barrier
	s_add_i32 s26, s52, s34
	v_lshl_add_u64 v[144:145], v[144:145], 0, s[8:9]
	s_mov_b32 m0, s26
	ds_read_b128 v[188:191], v151 offset:49152
	ds_read_b128 v[192:195], v151 offset:50176
	ds_read_b128 v[196:199], v151 offset:51200
	ds_read_b128 v[200:203], v151 offset:52224
	ds_read_b128 v[204:207], v151 offset:53248
	ds_read_b128 v[208:211], v151 offset:54272
	ds_read_b128 v[212:215], v151 offset:55296
	ds_read_b128 v[216:219], v151 offset:56320
	global_load_lds_dwordx4 v[144:145], off
	s_add_i32 m0, s26, 0x2000
	s_add_u32 s24, s24, 0x40080
	v_lshl_add_u64 v[144:145], v[180:181], 0, s[8:9]
	s_addc_u32 s25, s25, 0
	s_add_i32 s26, s53, s34
	global_load_lds_dwordx4 v[144:145], off
	v_lshl_add_u64 v[144:145], s[24:25], 0, v[130:131]
	s_mov_b32 m0, s26
	s_nop 0
	global_load_lds_dwordx4 v[144:145], off
	v_lshl_add_u64 v[144:145], s[24:25], 0, v[134:135]
	s_add_i32 m0, s26, 0x2000
	s_nop 0
	global_load_lds_dwordx4 v[144:145], off
	v_lshl_add_u64 v[144:145], v[220:221], 0, s[8:9]
	s_mov_b32 m0, s41
	s_nop 0
	global_load_lds_dwordx4 v[144:145], off
	v_lshl_add_u64 v[144:145], v[222:223], 0, s[8:9]
	s_mov_b32 m0, s42
	s_nop 0
	global_load_lds_dwordx4 v[144:145], off
	s_waitcnt vmcnt(8)
	s_waitcnt lgkmcnt(0)
	s_barrier
	s_setprio 1
	v_mfma_f32_16x16x32_bf16 v[60:63], v[152:155], v[188:191], v[60:63]
	v_mfma_f32_16x16x32_bf16 v[56:59], v[160:163], v[188:191], v[56:59]
	v_mfma_f32_16x16x32_bf16 v[44:47], v[152:155], v[196:199], v[44:47]
	v_mfma_f32_16x16x32_bf16 v[40:43], v[160:163], v[196:199], v[40:43]
	v_mfma_f32_16x16x32_bf16 v[28:31], v[152:155], v[204:207], v[28:31]
	v_mfma_f32_16x16x32_bf16 v[24:27], v[160:163], v[204:207], v[24:27]
	v_mfma_f32_16x16x32_bf16 v[12:15], v[152:155], v[212:215], v[12:15]
	v_mfma_f32_16x16x32_bf16 v[8:11], v[160:163], v[212:215], v[8:11]
	v_mfma_f32_16x16x32_bf16 v[60:63], v[156:159], v[192:195], v[60:63]
	v_mfma_f32_16x16x32_bf16 v[56:59], v[164:167], v[192:195], v[56:59]
	v_mfma_f32_16x16x32_bf16 v[44:47], v[156:159], v[200:203], v[44:47]
	v_mfma_f32_16x16x32_bf16 v[40:43], v[164:167], v[200:203], v[40:43]
	v_mfma_f32_16x16x32_bf16 v[28:31], v[156:159], v[208:211], v[28:31]
	v_mfma_f32_16x16x32_bf16 v[24:27], v[164:167], v[208:211], v[24:27]
	v_mfma_f32_16x16x32_bf16 v[12:15], v[156:159], v[216:219], v[12:15]
	v_mfma_f32_16x16x32_bf16 v[8:11], v[164:167], v[216:219], v[8:11]
	v_mfma_f32_16x16x32_bf16 v[52:55], v[168:171], v[188:191], v[52:55]
	v_mfma_f32_16x16x32_bf16 v[48:51], v[176:179], v[188:191], v[48:51]
	v_mfma_f32_16x16x32_bf16 v[36:39], v[168:171], v[196:199], v[36:39]
	v_mfma_f32_16x16x32_bf16 v[32:35], v[176:179], v[196:199], v[32:35]
	v_mfma_f32_16x16x32_bf16 v[20:23], v[168:171], v[204:207], v[20:23]
	v_mfma_f32_16x16x32_bf16 v[16:19], v[176:179], v[204:207], v[16:19]
	v_mfma_f32_16x16x32_bf16 v[4:7], v[168:171], v[212:215], v[4:7]
	v_mfma_f32_16x16x32_bf16 v[0:3], v[176:179], v[212:215], v[0:3]
	v_mfma_f32_16x16x32_bf16 v[52:55], v[172:175], v[192:195], v[52:55]
	v_mfma_f32_16x16x32_bf16 v[48:51], v[184:187], v[192:195], v[48:51]
	v_mfma_f32_16x16x32_bf16 v[36:39], v[172:175], v[200:203], v[36:39]
	v_mfma_f32_16x16x32_bf16 v[32:35], v[184:187], v[200:203], v[32:35]
	v_mfma_f32_16x16x32_bf16 v[20:23], v[172:175], v[208:211], v[20:23]
	v_mfma_f32_16x16x32_bf16 v[16:19], v[184:187], v[208:211], v[16:19]
	v_mfma_f32_16x16x32_bf16 v[4:7], v[172:175], v[216:219], v[4:7]
	v_mfma_f32_16x16x32_bf16 v[0:3], v[184:187], v[216:219], v[0:3]
	s_setprio 0
	s_barrier
	s_add_i32 s51, s51, 2
	s_add_u32 s22, s22, 0x100
	s_addc_u32 s23, s23, 0
	s_add_u32 s49, s49, 0x100
	s_addc_u32 s50, s50, 0

.LBB0_337:
	s_add_u32 s24, s24, 0xb0080
	s_addc_u32 s25, s25, 0
	s_add_u32 s55, s26, 0x100
	s_addc_u32 s56, s27, 0
	s_mov_b32 s57, -2
	ds_read_b128 v[150:153], v147
	ds_read_b128 v[154:157], v147 offset:1024
	ds_read_b128 v[158:161], v147 offset:2048
	ds_read_b128 v[162:165], v147 offset:3072
	ds_read_b128 v[166:169], v148
	ds_read_b128 v[170:173], v148 offset:1024
	ds_read_b128 v[174:177], v148 offset:2048
	ds_read_b128 v[178:181], v148 offset:3072
	s_add_u32 s26, s24, 0xfff50080
	s_addc_u32 s27, s25, -1
	s_cmp_eq_u32 s57, 40
	s_cselect_b32 s29, s5, s27
	s_cselect_b32 s28, s4, s26
	s_cselect_b32 s27, s23, s56
	s_cselect_b32 s26, s22, s55
	v_lshl_add_u64 v[216:217], s[24:25], 0, v[136:137]
	s_add_i32 m0, s37, 0xc000
	ds_read_b128 v[184:187], v149
	ds_read_b128 v[188:191], v149 offset:1024
	ds_read_b128 v[192:195], v149 offset:2048
	ds_read_b128 v[196:199], v149 offset:3072
	ds_read_b128 v[200:203], v149 offset:4096
	ds_read_b128 v[204:207], v149 offset:5120
	ds_read_b128 v[208:211], v149 offset:6144
	ds_read_b128 v[212:215], v149 offset:7168
	global_load_lds_dwordx4 v[216:217], off
	v_lshl_add_u64 v[216:217], s[24:25], 0, v[138:139]
	s_add_i32 m0, s37, 0xe000
	s_nop 0
	global_load_lds_dwordx4 v[216:217], off
	s_waitcnt vmcnt(8)
	s_waitcnt lgkmcnt(0)
	s_barrier
	s_setprio 1
	v_mfma_f32_16x16x32_bf16 v[124:127], v[150:153], v[184:187], 0
	v_mfma_f32_16x16x32_bf16 v[120:123], v[158:161], v[184:187], 0
	v_mfma_f32_16x16x32_bf16 v[116:119], v[150:153], v[192:195], 0
	v_mfma_f32_16x16x32_bf16 v[112:115], v[158:161], v[192:195], 0
	v_mfma_f32_16x16x32_bf16 v[100:103], v[150:153], v[200:203], 0
	v_mfma_f32_16x16x32_bf16 v[96:99], v[158:161], v[200:203], 0
	v_mfma_f32_16x16x32_bf16 v[84:87], v[150:153], v[208:211], 0
	v_mfma_f32_16x16x32_bf16 v[80:83], v[158:161], v[208:211], 0
	v_mfma_f32_16x16x32_bf16 v[124:127], v[154:157], v[188:191], v[124:127]
	v_mfma_f32_16x16x32_bf16 v[120:123], v[162:165], v[188:191], v[120:123]
	v_mfma_f32_16x16x32_bf16 v[116:119], v[154:157], v[196:199], v[116:119]
	v_mfma_f32_16x16x32_bf16 v[112:115], v[162:165], v[196:199], v[112:115]
	v_mfma_f32_16x16x32_bf16 v[100:103], v[154:157], v[204:207], v[100:103]
	v_mfma_f32_16x16x32_bf16 v[96:99], v[162:165], v[204:207], v[96:99]
	v_mfma_f32_16x16x32_bf16 v[84:87], v[154:157], v[212:215], v[84:87]
	v_mfma_f32_16x16x32_bf16 v[80:83], v[162:165], v[212:215], v[80:83]
	v_mfma_f32_16x16x32_bf16 v[108:111], v[166:169], v[184:187], 0
	v_mfma_f32_16x16x32_bf16 v[104:107], v[174:177], v[184:187], 0
	v_mfma_f32_16x16x32_bf16 v[92:95], v[166:169], v[192:195], 0
	v_mfma_f32_16x16x32_bf16 v[88:91], v[174:177], v[192:195], 0
	v_mfma_f32_16x16x32_bf16 v[76:79], v[166:169], v[200:203], 0
	v_mfma_f32_16x16x32_bf16 v[72:75], v[174:177], v[200:203], 0
	v_mfma_f32_16x16x32_bf16 v[68:71], v[166:169], v[208:211], 0
	v_mfma_f32_16x16x32_bf16 v[64:67], v[174:177], v[208:211], 0
	v_mfma_f32_16x16x32_bf16 v[108:111], v[170:173], v[188:191], v[108:111]
	v_mfma_f32_16x16x32_bf16 v[104:107], v[178:181], v[188:191], v[104:107]
	v_mfma_f32_16x16x32_bf16 v[92:95], v[170:173], v[196:199], v[92:95]
	v_mfma_f32_16x16x32_bf16 v[88:91], v[178:181], v[196:199], v[88:91]
	v_mfma_f32_16x16x32_bf16 v[76:79], v[170:173], v[204:207], v[76:79]
	v_mfma_f32_16x16x32_bf16 v[72:75], v[178:181], v[204:207], v[72:75]
	v_mfma_f32_16x16x32_bf16 v[68:71], v[170:173], v[212:215], v[68:71]
	v_mfma_f32_16x16x32_bf16 v[64:67], v[178:181], v[212:215], v[64:67]
	s_setprio 0
	s_barrier
	s_add_i32 s58, s45, s36
	v_lshl_add_u64 v[216:217], s[26:27], 0, v[130:131]
	s_mov_b32 m0, s58
	ds_read_b128 v[184:187], v149 offset:16384
	ds_read_b128 v[188:191], v149 offset:17408
	ds_read_b128 v[192:195], v149 offset:18432
	ds_read_b128 v[196:199], v149 offset:19456
	ds_read_b128 v[200:203], v149 offset:20480
	ds_read_b128 v[204:207], v149 offset:21504
	ds_read_b128 v[208:211], v149 offset:22528
	ds_read_b128 v[212:215], v149 offset:23552
	global_load_lds_dwordx4 v[216:217], off
	s_add_i32 m0, s58, 0x2000
	s_add_u32 s58, s26, 0xb0000
	v_lshl_add_u64 v[218:219], s[26:27], 0, v[134:135]
	s_addc_u32 s59, s27, 0
	s_add_i32 s60, s46, s36
	global_load_lds_dwordx4 v[218:219], off
	v_lshl_add_u64 v[220:221], s[58:59], 0, v[130:131]
	s_mov_b32 m0, s60
	v_lshl_add_u64 v[222:223], s[28:29], 0, v[132:133]
	global_load_lds_dwordx4 v[220:221], off
	v_lshl_add_u64 v[220:221], s[58:59], 0, v[134:135]
	s_add_i32 m0, s60, 0x2000
	s_nop 0
	global_load_lds_dwordx4 v[220:221], off
	v_lshl_add_u64 v[220:221], s[28:29], 0, v[128:129]
	s_mov_b32 m0, s37
	s_nop 0
	global_load_lds_dwordx4 v[220:221], off
	s_mov_b32 m0, s38
	s_nop 0
	global_load_lds_dwordx4 v[222:223], off
	s_waitcnt vmcnt(8)
	s_waitcnt lgkmcnt(0)
	s_barrier
	s_setprio 1
	v_mfma_f32_16x16x32_bf16 v[60:63], v[150:153], v[184:187], 0
	v_mfma_f32_16x16x32_bf16 v[56:59], v[158:161], v[184:187], 0
	v_mfma_f32_16x16x32_bf16 v[52:55], v[150:153], v[192:195], 0
	v_mfma_f32_16x16x32_bf16 v[48:51], v[158:161], v[192:195], 0
	v_mfma_f32_16x16x32_bf16 v[36:39], v[150:153], v[200:203], 0
	v_mfma_f32_16x16x32_bf16 v[32:35], v[158:161], v[200:203], 0
	v_mfma_f32_16x16x32_bf16 v[20:23], v[150:153], v[208:211], 0
	v_mfma_f32_16x16x32_bf16 v[16:19], v[158:161], v[208:211], 0
	v_mfma_f32_16x16x32_bf16 v[60:63], v[154:157], v[188:191], v[60:63]
	v_mfma_f32_16x16x32_bf16 v[56:59], v[162:165], v[188:191], v[56:59]
	v_mfma_f32_16x16x32_bf16 v[52:55], v[154:157], v[196:199], v[52:55]
	v_mfma_f32_16x16x32_bf16 v[48:51], v[162:165], v[196:199], v[48:51]
	v_mfma_f32_16x16x32_bf16 v[36:39], v[154:157], v[204:207], v[36:39]
	v_mfma_f32_16x16x32_bf16 v[32:35], v[162:165], v[204:207], v[32:35]
	v_mfma_f32_16x16x32_bf16 v[20:23], v[154:157], v[212:215], v[20:23]
	v_mfma_f32_16x16x32_bf16 v[16:19], v[162:165], v[212:215], v[16:19]
	v_mfma_f32_16x16x32_bf16 v[44:47], v[166:169], v[184:187], 0
	v_mfma_f32_16x16x32_bf16 v[40:43], v[174:177], v[184:187], 0
	v_mfma_f32_16x16x32_bf16 v[28:31], v[166:169], v[192:195], 0
	v_mfma_f32_16x16x32_bf16 v[24:27], v[174:177], v[192:195], 0
	v_mfma_f32_16x16x32_bf16 v[12:15], v[166:169], v[200:203], 0
	v_mfma_f32_16x16x32_bf16 v[8:11], v[174:177], v[200:203], 0
	v_mfma_f32_16x16x32_bf16 v[4:7], v[166:169], v[208:211], 0
	v_mfma_f32_16x16x32_bf16 v[0:3], v[174:177], v[208:211], 0
	v_mfma_f32_16x16x32_bf16 v[44:47], v[170:173], v[188:191], v[44:47]
	v_mfma_f32_16x16x32_bf16 v[40:43], v[178:181], v[188:191], v[40:43]
	v_mfma_f32_16x16x32_bf16 v[28:31], v[170:173], v[196:199], v[28:31]
	v_mfma_f32_16x16x32_bf16 v[24:27], v[178:181], v[196:199], v[24:27]
	v_mfma_f32_16x16x32_bf16 v[12:15], v[170:173], v[204:207], v[12:15]
	v_mfma_f32_16x16x32_bf16 v[8:11], v[178:181], v[204:207], v[8:11]
	v_mfma_f32_16x16x32_bf16 v[4:7], v[170:173], v[212:215], v[4:7]
	v_mfma_f32_16x16x32_bf16 v[0:3], v[178:181], v[212:215], v[0:3]
	s_setprio 0
	s_barrier
	s_add_i32 s58, 0, 0x18000
	s_add_i32 s59, 0, 0x1c000
	v_add_u32_e32 v162, s58, v145
	v_add_u32_e32 v178, s59, v145
	ds_read_b128 v[150:153], v162
	ds_read_b128 v[154:157], v162 offset:1024
	ds_read_b128 v[158:161], v162 offset:2048
	ds_read_b128 v[162:165], v162 offset:3072
	ds_read_b128 v[166:169], v178
	ds_read_b128 v[170:173], v178 offset:1024
	ds_read_b128 v[174:177], v178 offset:2048
	ds_read_b128 v[178:181], v178 offset:3072
	s_add_u32 s28, s28, 0xb0000
	s_addc_u32 s29, s29, 0
	s_mov_b32 m0, s39
	v_lshl_add_u64 v[224:225], s[28:29], 0, v[128:129]
	ds_read_b128 v[184:187], v149 offset:32768
	ds_read_b128 v[188:191], v149 offset:33792
	ds_read_b128 v[192:195], v149 offset:34816
	ds_read_b128 v[196:199], v149 offset:35840
	ds_read_b128 v[200:203], v149 offset:36864
	ds_read_b128 v[204:207], v149 offset:37888
	ds_read_b128 v[208:211], v149 offset:38912
	ds_read_b128 v[212:215], v149 offset:39936
	global_load_lds_dwordx4 v[224:225], off
	v_lshl_add_u64 v[224:225], s[28:29], 0, v[132:133]
	s_mov_b32 m0, s40
	s_nop 0
	global_load_lds_dwordx4 v[224:225], off
	s_waitcnt vmcnt(8)
	s_waitcnt lgkmcnt(0)
	s_barrier
	s_setprio 1
	v_mfma_f32_16x16x32_bf16 v[124:127], v[150:153], v[184:187], v[124:127]
	v_mfma_f32_16x16x32_bf16 v[120:123], v[158:161], v[184:187], v[120:123]
	v_mfma_f32_16x16x32_bf16 v[116:119], v[150:153], v[192:195], v[116:119]
	v_mfma_f32_16x16x32_bf16 v[112:115], v[158:161], v[192:195], v[112:115]
	v_mfma_f32_16x16x32_bf16 v[100:103], v[150:153], v[200:203], v[100:103]
	v_mfma_f32_16x16x32_bf16 v[96:99], v[158:161], v[200:203], v[96:99]
	v_mfma_f32_16x16x32_bf16 v[84:87], v[150:153], v[208:211], v[84:87]
	v_mfma_f32_16x16x32_bf16 v[80:83], v[158:161], v[208:211], v[80:83]
	v_mfma_f32_16x16x32_bf16 v[124:127], v[154:157], v[188:191], v[124:127]
	v_mfma_f32_16x16x32_bf16 v[120:123], v[162:165], v[188:191], v[120:123]
	v_mfma_f32_16x16x32_bf16 v[116:119], v[154:157], v[196:199], v[116:119]
	v_mfma_f32_16x16x32_bf16 v[112:115], v[162:165], v[196:199], v[112:115]
	v_mfma_f32_16x16x32_bf16 v[100:103], v[154:157], v[204:207], v[100:103]
	v_mfma_f32_16x16x32_bf16 v[96:99], v[162:165], v[204:207], v[96:99]
	v_mfma_f32_16x16x32_bf16 v[84:87], v[154:157], v[212:215], v[84:87]
	v_mfma_f32_16x16x32_bf16 v[80:83], v[162:165], v[212:215], v[80:83]
	v_mfma_f32_16x16x32_bf16 v[108:111], v[166:169], v[184:187], v[108:111]
	v_mfma_f32_16x16x32_bf16 v[104:107], v[174:177], v[184:187], v[104:107]
	v_mfma_f32_16x16x32_bf16 v[92:95], v[166:169], v[192:195], v[92:95]
	v_mfma_f32_16x16x32_bf16 v[88:91], v[174:177], v[192:195], v[88:91]
	v_mfma_f32_16x16x32_bf16 v[76:79], v[166:169], v[200:203], v[76:79]
	v_mfma_f32_16x16x32_bf16 v[72:75], v[174:177], v[200:203], v[72:75]
	v_mfma_f32_16x16x32_bf16 v[68:71], v[166:169], v[208:211], v[68:71]
	v_mfma_f32_16x16x32_bf16 v[64:67], v[174:177], v[208:211], v[64:67]
	v_mfma_f32_16x16x32_bf16 v[108:111], v[170:173], v[188:191], v[108:111]
	v_mfma_f32_16x16x32_bf16 v[104:107], v[178:181], v[188:191], v[104:107]
	v_mfma_f32_16x16x32_bf16 v[92:95], v[170:173], v[196:199], v[92:95]
	v_mfma_f32_16x16x32_bf16 v[88:91], v[178:181], v[196:199], v[88:91]
	v_mfma_f32_16x16x32_bf16 v[76:79], v[170:173], v[204:207], v[76:79]
	v_mfma_f32_16x16x32_bf16 v[72:75], v[178:181], v[204:207], v[72:75]
	v_mfma_f32_16x16x32_bf16 v[68:71], v[170:173], v[212:215], v[68:71]
	v_mfma_f32_16x16x32_bf16 v[64:67], v[178:181], v[212:215], v[64:67]
	s_setprio 0
	s_barrier
	s_add_i32 s28, s58, s36
	v_lshl_add_u64 v[216:217], v[216:217], 0, s[10:11]
	s_mov_b32 m0, s28
	ds_read_b128 v[184:187], v149 offset:49152
	ds_read_b128 v[188:191], v149 offset:50176
	ds_read_b128 v[192:195], v149 offset:51200
	ds_read_b128 v[196:199], v149 offset:52224
	ds_read_b128 v[200:203], v149 offset:53248
	ds_read_b128 v[204:207], v149 offset:54272
	ds_read_b128 v[208:211], v149 offset:55296
	ds_read_b128 v[212:215], v149 offset:56320
	global_load_lds_dwordx4 v[216:217], off
	s_add_i32 m0, s28, 0x2000
	s_add_u32 s26, s26, 0xb0080
	v_lshl_add_u64 v[216:217], v[218:219], 0, s[10:11]
	s_addc_u32 s27, s27, 0
	s_add_i32 s28, s59, s36
	global_load_lds_dwordx4 v[216:217], off
	v_lshl_add_u64 v[216:217], s[26:27], 0, v[130:131]
	s_mov_b32 m0, s28
	s_nop 0
	global_load_lds_dwordx4 v[216:217], off
	v_lshl_add_u64 v[216:217], s[26:27], 0, v[134:135]
	s_add_i32 m0, s28, 0x2000
	s_nop 0
	global_load_lds_dwordx4 v[216:217], off
	v_lshl_add_u64 v[216:217], v[220:221], 0, s[10:11]
	s_mov_b32 m0, s43
	s_nop 0
	global_load_lds_dwordx4 v[216:217], off
	v_lshl_add_u64 v[216:217], v[222:223], 0, s[10:11]
	s_mov_b32 m0, s44
	s_nop 0
	global_load_lds_dwordx4 v[216:217], off
	s_waitcnt vmcnt(8)
	s_waitcnt lgkmcnt(0)
	s_barrier
	s_setprio 1
	v_mfma_f32_16x16x32_bf16 v[60:63], v[150:153], v[184:187], v[60:63]
	v_mfma_f32_16x16x32_bf16 v[56:59], v[158:161], v[184:187], v[56:59]
	v_mfma_f32_16x16x32_bf16 v[52:55], v[150:153], v[192:195], v[52:55]
	v_mfma_f32_16x16x32_bf16 v[48:51], v[158:161], v[192:195], v[48:51]
	v_mfma_f32_16x16x32_bf16 v[36:39], v[150:153], v[200:203], v[36:39]
	v_mfma_f32_16x16x32_bf16 v[32:35], v[158:161], v[200:203], v[32:35]
	v_mfma_f32_16x16x32_bf16 v[20:23], v[150:153], v[208:211], v[20:23]
	v_mfma_f32_16x16x32_bf16 v[16:19], v[158:161], v[208:211], v[16:19]
	v_mfma_f32_16x16x32_bf16 v[60:63], v[154:157], v[188:191], v[60:63]
	v_mfma_f32_16x16x32_bf16 v[56:59], v[162:165], v[188:191], v[56:59]
	v_mfma_f32_16x16x32_bf16 v[52:55], v[154:157], v[196:199], v[52:55]
	v_mfma_f32_16x16x32_bf16 v[48:51], v[162:165], v[196:199], v[48:51]
	v_mfma_f32_16x16x32_bf16 v[36:39], v[154:157], v[204:207], v[36:39]
	v_mfma_f32_16x16x32_bf16 v[32:35], v[162:165], v[204:207], v[32:35]
	v_mfma_f32_16x16x32_bf16 v[20:23], v[154:157], v[212:215], v[20:23]
	v_mfma_f32_16x16x32_bf16 v[16:19], v[162:165], v[212:215], v[16:19]
	v_mfma_f32_16x16x32_bf16 v[44:47], v[166:169], v[184:187], v[44:47]
	v_mfma_f32_16x16x32_bf16 v[40:43], v[174:177], v[184:187], v[40:43]
	v_mfma_f32_16x16x32_bf16 v[28:31], v[166:169], v[192:195], v[28:31]
	v_mfma_f32_16x16x32_bf16 v[24:27], v[174:177], v[192:195], v[24:27]
	v_mfma_f32_16x16x32_bf16 v[12:15], v[166:169], v[200:203], v[12:15]
	v_mfma_f32_16x16x32_bf16 v[8:11], v[174:177], v[200:203], v[8:11]
	v_mfma_f32_16x16x32_bf16 v[4:7], v[166:169], v[208:211], v[4:7]
	v_mfma_f32_16x16x32_bf16 v[0:3], v[174:177], v[208:211], v[0:3]
	v_mfma_f32_16x16x32_bf16 v[44:47], v[170:173], v[188:191], v[44:47]
	v_mfma_f32_16x16x32_bf16 v[40:43], v[178:181], v[188:191], v[40:43]
	v_mfma_f32_16x16x32_bf16 v[28:31], v[170:173], v[196:199], v[28:31]
	v_mfma_f32_16x16x32_bf16 v[24:27], v[178:181], v[196:199], v[24:27]
	v_mfma_f32_16x16x32_bf16 v[12:15], v[170:173], v[204:207], v[12:15]
	v_mfma_f32_16x16x32_bf16 v[8:11], v[178:181], v[204:207], v[8:11]
	v_mfma_f32_16x16x32_bf16 v[4:7], v[170:173], v[212:215], v[4:7]
	v_mfma_f32_16x16x32_bf16 v[0:3], v[178:181], v[212:215], v[0:3]
	s_setprio 0
	s_barrier
	s_add_i32 s57, s57, 2
	s_add_u32 s24, s24, 0x100
	s_addc_u32 s25, s25, 0
	s_add_u32 s55, s55, 0x100
	s_addc_u32 s56, s56, 0

.LBB0_474:
	s_ashr_i32 s39, s38, 31
	s_lshl_b64 s[40:41], s[38:39], 19
	s_add_u32 s40, s52, s40
	s_addc_u32 s41, s53, s41
	s_and_b64 s[42:43], s[6:7], exec
	s_cselect_b32 s1, s41, s47
	s_cselect_b32 s39, s40, s46
	s_ashr_i32 s37, s36, 31
	s_lshl_b64 s[42:43], s[36:37], 19
	s_add_u32 s42, s54, s42
	s_addc_u32 s43, s55, s43
	s_and_b64 s[50:51], s[6:7], exec
	s_cselect_b32 s37, s43, s49
	s_cselect_b32 s45, s42, s48
	s_add_u32 s46, s46, 0x40080
	s_addc_u32 s47, s47, 0
	s_add_u32 s75, s48, 0x100
	s_addc_u32 s76, s49, 0
	s_mov_b32 s77, -2
	ds_read_b128 v[150:153], v158
	ds_read_b128 v[162:165], v158 offset:1024
	ds_read_b128 v[166:169], v158 offset:2048
	ds_read_b128 v[170:173], v158 offset:3072
	ds_read_b128 v[174:177], v159
	ds_read_b128 v[178:181], v159 offset:1024
	ds_read_b128 v[184:187], v159 offset:2048
	ds_read_b128 v[188:191], v159 offset:3072
	s_add_u32 s48, s46, 0xfffc0080
	s_addc_u32 s49, s47, -1
	s_cmp_eq_u32 s77, 12
	s_cselect_b32 s51, s1, s49
	s_cselect_b32 s50, s39, s48
	s_cselect_b32 s49, s37, s76
	s_cselect_b32 s48, s45, s75
	v_lshl_add_u64 v[224:225], s[46:47], 0, v[142:143]
	s_add_i32 m0, s57, 0xc000
	ds_read_b128 v[192:195], v160
	ds_read_b128 v[196:199], v160 offset:1024
	ds_read_b128 v[200:203], v160 offset:2048
	ds_read_b128 v[204:207], v160 offset:3072
	ds_read_b128 v[208:211], v160 offset:4096
	ds_read_b128 v[212:215], v160 offset:5120
	ds_read_b128 v[216:219], v160 offset:6144
	ds_read_b128 v[220:223], v160 offset:7168
	global_load_lds_dwordx4 v[224:225], off
	v_lshl_add_u64 v[224:225], s[46:47], 0, v[144:145]
	s_add_i32 m0, s57, 0xe000
	s_nop 0
	global_load_lds_dwordx4 v[224:225], off
	s_waitcnt vmcnt(8)
	s_waitcnt lgkmcnt(0)
	s_barrier
	s_setprio 1
	v_mfma_f32_16x16x32_bf16 v[64:67], v[150:153], v[192:195], 0
	v_mfma_f32_16x16x32_bf16 v[28:31], v[166:169], v[192:195], 0
	v_mfma_f32_16x16x32_bf16 v[60:63], v[150:153], v[200:203], 0
	v_mfma_f32_16x16x32_bf16 v[24:27], v[166:169], v[200:203], 0
	v_mfma_f32_16x16x32_bf16 v[56:59], v[150:153], v[208:211], 0
	v_mfma_f32_16x16x32_bf16 v[20:23], v[166:169], v[208:211], 0
	v_mfma_f32_16x16x32_bf16 v[52:55], v[150:153], v[216:219], 0
	v_mfma_f32_16x16x32_bf16 v[16:19], v[166:169], v[216:219], 0
	v_mfma_f32_16x16x32_bf16 v[64:67], v[162:165], v[196:199], v[64:67]
	v_mfma_f32_16x16x32_bf16 v[28:31], v[170:173], v[196:199], v[28:31]
	v_mfma_f32_16x16x32_bf16 v[60:63], v[162:165], v[204:207], v[60:63]
	v_mfma_f32_16x16x32_bf16 v[24:27], v[170:173], v[204:207], v[24:27]
	v_mfma_f32_16x16x32_bf16 v[56:59], v[162:165], v[212:215], v[56:59]
	v_mfma_f32_16x16x32_bf16 v[20:23], v[170:173], v[212:215], v[20:23]
	v_mfma_f32_16x16x32_bf16 v[52:55], v[162:165], v[220:223], v[52:55]
	v_mfma_f32_16x16x32_bf16 v[16:19], v[170:173], v[220:223], v[16:19]
	v_mfma_f32_16x16x32_bf16 v[124:127], v[174:177], v[192:195], 0
	v_mfma_f32_16x16x32_bf16 v[120:123], v[184:187], v[192:195], 0
	v_mfma_f32_16x16x32_bf16 v[116:119], v[174:177], v[200:203], 0
	v_mfma_f32_16x16x32_bf16 v[112:115], v[184:187], v[200:203], 0
	v_mfma_f32_16x16x32_bf16 v[108:111], v[174:177], v[208:211], 0
	v_mfma_f32_16x16x32_bf16 v[104:107], v[184:187], v[208:211], 0
	v_mfma_f32_16x16x32_bf16 v[100:103], v[174:177], v[216:219], 0
	v_mfma_f32_16x16x32_bf16 v[96:99], v[184:187], v[216:219], 0
	v_mfma_f32_16x16x32_bf16 v[124:127], v[178:181], v[196:199], v[124:127]
	v_mfma_f32_16x16x32_bf16 v[120:123], v[188:191], v[196:199], v[120:123]
	v_mfma_f32_16x16x32_bf16 v[116:119], v[178:181], v[204:207], v[116:119]
	v_mfma_f32_16x16x32_bf16 v[112:115], v[188:191], v[204:207], v[112:115]
	v_mfma_f32_16x16x32_bf16 v[108:111], v[178:181], v[212:215], v[108:111]
	v_mfma_f32_16x16x32_bf16 v[104:107], v[188:191], v[212:215], v[104:107]
	v_mfma_f32_16x16x32_bf16 v[100:103], v[178:181], v[220:223], v[100:103]
	v_mfma_f32_16x16x32_bf16 v[96:99], v[188:191], v[220:223], v[96:99]
	s_setprio 0
	s_barrier
	s_add_i32 s78, s66, s56
	v_lshl_add_u64 v[224:225], s[48:49], 0, v[130:131]
	s_mov_b32 m0, s78
	ds_read_b128 v[192:195], v160 offset:16384
	ds_read_b128 v[196:199], v160 offset:17408
	ds_read_b128 v[200:203], v160 offset:18432
	ds_read_b128 v[204:207], v160 offset:19456
	ds_read_b128 v[208:211], v160 offset:20480
	ds_read_b128 v[212:215], v160 offset:21504
	ds_read_b128 v[216:219], v160 offset:22528
	ds_read_b128 v[220:223], v160 offset:23552
	global_load_lds_dwordx4 v[224:225], off
	s_add_i32 m0, s78, 0x2000
	s_add_u32 s78, s48, 0x40000
	v_lshl_add_u64 v[226:227], s[48:49], 0, v[134:135]
	s_addc_u32 s79, s49, 0
	s_add_i32 s80, s67, s56
	global_load_lds_dwordx4 v[226:227], off
	v_lshl_add_u64 v[228:229], s[78:79], 0, v[130:131]
	s_mov_b32 m0, s80
	v_lshl_add_u64 v[230:231], s[50:51], 0, v[132:133]
	global_load_lds_dwordx4 v[228:229], off
	v_lshl_add_u64 v[228:229], s[78:79], 0, v[134:135]
	s_add_i32 m0, s80, 0x2000
	s_nop 0
	global_load_lds_dwordx4 v[228:229], off
	v_lshl_add_u64 v[228:229], s[50:51], 0, v[128:129]
	s_mov_b32 m0, s57
	s_nop 0
	global_load_lds_dwordx4 v[228:229], off
	s_mov_b32 m0, s58
	s_nop 0
	global_load_lds_dwordx4 v[230:231], off
	s_waitcnt vmcnt(8)
	s_waitcnt lgkmcnt(0)
	s_barrier
	s_setprio 1
	v_mfma_f32_16x16x32_bf16 v[44:47], v[150:153], v[192:195], 0
	v_mfma_f32_16x16x32_bf16 v[12:15], v[166:169], v[192:195], 0
	v_mfma_f32_16x16x32_bf16 v[40:43], v[150:153], v[200:203], 0
	v_mfma_f32_16x16x32_bf16 v[8:11], v[166:169], v[200:203], 0
	v_mfma_f32_16x16x32_bf16 v[36:39], v[150:153], v[208:211], 0
	v_mfma_f32_16x16x32_bf16 v[4:7], v[166:169], v[208:211], 0
	v_mfma_f32_16x16x32_bf16 v[32:35], v[150:153], v[216:219], 0
	v_mfma_f32_16x16x32_bf16 v[0:3], v[166:169], v[216:219], 0
	v_mfma_f32_16x16x32_bf16 v[44:47], v[162:165], v[196:199], v[44:47]
	v_mfma_f32_16x16x32_bf16 v[12:15], v[170:173], v[196:199], v[12:15]
	v_mfma_f32_16x16x32_bf16 v[40:43], v[162:165], v[204:207], v[40:43]
	v_mfma_f32_16x16x32_bf16 v[8:11], v[170:173], v[204:207], v[8:11]
	v_mfma_f32_16x16x32_bf16 v[36:39], v[162:165], v[212:215], v[36:39]
	v_mfma_f32_16x16x32_bf16 v[4:7], v[170:173], v[212:215], v[4:7]
	v_mfma_f32_16x16x32_bf16 v[32:35], v[162:165], v[220:223], v[32:35]
	v_mfma_f32_16x16x32_bf16 v[0:3], v[170:173], v[220:223], v[0:3]
	v_mfma_f32_16x16x32_bf16 v[92:95], v[174:177], v[192:195], 0
	v_mfma_f32_16x16x32_bf16 v[88:91], v[184:187], v[192:195], 0
	v_mfma_f32_16x16x32_bf16 v[84:87], v[174:177], v[200:203], 0
	v_mfma_f32_16x16x32_bf16 v[80:83], v[184:187], v[200:203], 0
	v_mfma_f32_16x16x32_bf16 v[76:79], v[174:177], v[208:211], 0
	v_mfma_f32_16x16x32_bf16 v[72:75], v[184:187], v[208:211], 0
	v_mfma_f32_16x16x32_bf16 v[68:71], v[174:177], v[216:219], 0
	v_mfma_f32_16x16x32_bf16 v[48:51], v[184:187], v[216:219], 0
	v_mfma_f32_16x16x32_bf16 v[92:95], v[178:181], v[196:199], v[92:95]
	v_mfma_f32_16x16x32_bf16 v[88:91], v[188:191], v[196:199], v[88:91]
	v_mfma_f32_16x16x32_bf16 v[84:87], v[178:181], v[204:207], v[84:87]
	v_mfma_f32_16x16x32_bf16 v[80:83], v[188:191], v[204:207], v[80:83]
	v_mfma_f32_16x16x32_bf16 v[76:79], v[178:181], v[212:215], v[76:79]
	v_mfma_f32_16x16x32_bf16 v[72:75], v[188:191], v[212:215], v[72:75]
	v_mfma_f32_16x16x32_bf16 v[68:71], v[178:181], v[220:223], v[68:71]
	v_mfma_f32_16x16x32_bf16 v[48:51], v[188:191], v[220:223], v[48:51]
	s_setprio 0
	s_barrier
	s_add_i32 s78, 0, 0x18000
	v_add_u32_e32 v136, s78, v156
	s_add_i32 s79, 0, 0x1c000
	ds_read_b128 v[150:153], v136
	ds_read_b128 v[162:165], v136 offset:1024
	ds_read_b128 v[166:169], v136 offset:2048
	ds_read_b128 v[170:173], v136 offset:3072
	v_add_u32_e32 v136, s79, v156
	ds_read_b128 v[174:177], v136
	ds_read_b128 v[178:181], v136 offset:1024
	ds_read_b128 v[184:187], v136 offset:2048
	ds_read_b128 v[188:191], v136 offset:3072
	s_add_u32 s50, s50, 0x40000
	s_addc_u32 s51, s51, 0
	s_mov_b32 m0, s59
	v_lshl_add_u64 v[232:233], s[50:51], 0, v[128:129]
	ds_read_b128 v[192:195], v160 offset:32768
	ds_read_b128 v[196:199], v160 offset:33792
	ds_read_b128 v[200:203], v160 offset:34816
	ds_read_b128 v[204:207], v160 offset:35840
	ds_read_b128 v[208:211], v160 offset:36864
	ds_read_b128 v[212:215], v160 offset:37888
	ds_read_b128 v[216:219], v160 offset:38912
	ds_read_b128 v[220:223], v160 offset:39936
	global_load_lds_dwordx4 v[232:233], off
	v_lshl_add_u64 v[232:233], s[50:51], 0, v[132:133]
	s_mov_b32 m0, s60
	s_nop 0
	global_load_lds_dwordx4 v[232:233], off
	s_waitcnt vmcnt(8)
	s_waitcnt lgkmcnt(0)
	s_barrier
	s_setprio 1
	v_mfma_f32_16x16x32_bf16 v[64:67], v[150:153], v[192:195], v[64:67]
	v_mfma_f32_16x16x32_bf16 v[28:31], v[166:169], v[192:195], v[28:31]
	v_mfma_f32_16x16x32_bf16 v[60:63], v[150:153], v[200:203], v[60:63]
	v_mfma_f32_16x16x32_bf16 v[24:27], v[166:169], v[200:203], v[24:27]
	v_mfma_f32_16x16x32_bf16 v[56:59], v[150:153], v[208:211], v[56:59]
	v_mfma_f32_16x16x32_bf16 v[20:23], v[166:169], v[208:211], v[20:23]
	v_mfma_f32_16x16x32_bf16 v[52:55], v[150:153], v[216:219], v[52:55]
	v_mfma_f32_16x16x32_bf16 v[16:19], v[166:169], v[216:219], v[16:19]
	v_mfma_f32_16x16x32_bf16 v[64:67], v[162:165], v[196:199], v[64:67]
	v_mfma_f32_16x16x32_bf16 v[28:31], v[170:173], v[196:199], v[28:31]
	v_mfma_f32_16x16x32_bf16 v[60:63], v[162:165], v[204:207], v[60:63]
	v_mfma_f32_16x16x32_bf16 v[24:27], v[170:173], v[204:207], v[24:27]
	v_mfma_f32_16x16x32_bf16 v[56:59], v[162:165], v[212:215], v[56:59]
	v_mfma_f32_16x16x32_bf16 v[20:23], v[170:173], v[212:215], v[20:23]
	v_mfma_f32_16x16x32_bf16 v[52:55], v[162:165], v[220:223], v[52:55]
	v_mfma_f32_16x16x32_bf16 v[16:19], v[170:173], v[220:223], v[16:19]
	v_mfma_f32_16x16x32_bf16 v[124:127], v[174:177], v[192:195], v[124:127]
	v_mfma_f32_16x16x32_bf16 v[120:123], v[184:187], v[192:195], v[120:123]
	v_mfma_f32_16x16x32_bf16 v[116:119], v[174:177], v[200:203], v[116:119]
	v_mfma_f32_16x16x32_bf16 v[112:115], v[184:187], v[200:203], v[112:115]
	v_mfma_f32_16x16x32_bf16 v[108:111], v[174:177], v[208:211], v[108:111]
	v_mfma_f32_16x16x32_bf16 v[104:107], v[184:187], v[208:211], v[104:107]
	v_mfma_f32_16x16x32_bf16 v[100:103], v[174:177], v[216:219], v[100:103]
	v_mfma_f32_16x16x32_bf16 v[96:99], v[184:187], v[216:219], v[96:99]
	v_mfma_f32_16x16x32_bf16 v[124:127], v[178:181], v[196:199], v[124:127]
	v_mfma_f32_16x16x32_bf16 v[120:123], v[188:191], v[196:199], v[120:123]
	v_mfma_f32_16x16x32_bf16 v[116:119], v[178:181], v[204:207], v[116:119]
	v_mfma_f32_16x16x32_bf16 v[112:115], v[188:191], v[204:207], v[112:115]
	v_mfma_f32_16x16x32_bf16 v[108:111], v[178:181], v[212:215], v[108:111]
	v_mfma_f32_16x16x32_bf16 v[104:107], v[188:191], v[212:215], v[104:107]
	v_mfma_f32_16x16x32_bf16 v[100:103], v[178:181], v[220:223], v[100:103]
	v_mfma_f32_16x16x32_bf16 v[96:99], v[188:191], v[220:223], v[96:99]
	s_setprio 0
	s_barrier
	s_add_i32 s50, s78, s56
	v_lshl_add_u64 v[224:225], v[224:225], 0, s[28:29]
	s_mov_b32 m0, s50
	ds_read_b128 v[192:195], v160 offset:49152
	ds_read_b128 v[196:199], v160 offset:50176
	ds_read_b128 v[200:203], v160 offset:51200
	ds_read_b128 v[204:207], v160 offset:52224
	ds_read_b128 v[208:211], v160 offset:53248
	ds_read_b128 v[212:215], v160 offset:54272
	ds_read_b128 v[216:219], v160 offset:55296
	ds_read_b128 v[220:223], v160 offset:56320
	global_load_lds_dwordx4 v[224:225], off
	s_add_i32 m0, s50, 0x2000
	s_add_u32 s48, s48, 0x40080
	v_lshl_add_u64 v[224:225], v[226:227], 0, s[28:29]
	s_addc_u32 s49, s49, 0
	s_add_i32 s50, s79, s56
	global_load_lds_dwordx4 v[224:225], off
	v_lshl_add_u64 v[224:225], s[48:49], 0, v[130:131]
	s_mov_b32 m0, s50
	s_nop 0
	global_load_lds_dwordx4 v[224:225], off
	v_lshl_add_u64 v[224:225], s[48:49], 0, v[134:135]
	s_add_i32 m0, s50, 0x2000
	s_nop 0
	global_load_lds_dwordx4 v[224:225], off
	v_lshl_add_u64 v[224:225], v[228:229], 0, s[28:29]
	s_mov_b32 m0, s63
	s_nop 0
	global_load_lds_dwordx4 v[224:225], off
	v_lshl_add_u64 v[224:225], v[230:231], 0, s[28:29]
	s_mov_b32 m0, s64
	s_nop 0
	global_load_lds_dwordx4 v[224:225], off
	s_waitcnt vmcnt(8)
	s_waitcnt lgkmcnt(0)
	s_barrier
	s_setprio 1
	v_mfma_f32_16x16x32_bf16 v[44:47], v[150:153], v[192:195], v[44:47]
	v_mfma_f32_16x16x32_bf16 v[12:15], v[166:169], v[192:195], v[12:15]
	v_mfma_f32_16x16x32_bf16 v[40:43], v[150:153], v[200:203], v[40:43]
	v_mfma_f32_16x16x32_bf16 v[8:11], v[166:169], v[200:203], v[8:11]
	v_mfma_f32_16x16x32_bf16 v[36:39], v[150:153], v[208:211], v[36:39]
	v_mfma_f32_16x16x32_bf16 v[4:7], v[166:169], v[208:211], v[4:7]
	v_mfma_f32_16x16x32_bf16 v[32:35], v[150:153], v[216:219], v[32:35]
	v_mfma_f32_16x16x32_bf16 v[0:3], v[166:169], v[216:219], v[0:3]
	v_mfma_f32_16x16x32_bf16 v[44:47], v[162:165], v[196:199], v[44:47]
	v_mfma_f32_16x16x32_bf16 v[12:15], v[170:173], v[196:199], v[12:15]
	v_mfma_f32_16x16x32_bf16 v[40:43], v[162:165], v[204:207], v[40:43]
	v_mfma_f32_16x16x32_bf16 v[8:11], v[170:173], v[204:207], v[8:11]
	v_mfma_f32_16x16x32_bf16 v[36:39], v[162:165], v[212:215], v[36:39]
	v_mfma_f32_16x16x32_bf16 v[4:7], v[170:173], v[212:215], v[4:7]
	v_mfma_f32_16x16x32_bf16 v[32:35], v[162:165], v[220:223], v[32:35]
	v_mfma_f32_16x16x32_bf16 v[0:3], v[170:173], v[220:223], v[0:3]
	v_mfma_f32_16x16x32_bf16 v[92:95], v[174:177], v[192:195], v[92:95]
	v_mfma_f32_16x16x32_bf16 v[88:91], v[184:187], v[192:195], v[88:91]
	v_mfma_f32_16x16x32_bf16 v[84:87], v[174:177], v[200:203], v[84:87]
	v_mfma_f32_16x16x32_bf16 v[80:83], v[184:187], v[200:203], v[80:83]
	v_mfma_f32_16x16x32_bf16 v[76:79], v[174:177], v[208:211], v[76:79]
	v_mfma_f32_16x16x32_bf16 v[72:75], v[184:187], v[208:211], v[72:75]
	v_mfma_f32_16x16x32_bf16 v[68:71], v[174:177], v[216:219], v[68:71]
	v_mfma_f32_16x16x32_bf16 v[48:51], v[184:187], v[216:219], v[48:51]
	v_mfma_f32_16x16x32_bf16 v[92:95], v[178:181], v[196:199], v[92:95]
	v_mfma_f32_16x16x32_bf16 v[88:91], v[188:191], v[196:199], v[88:91]
	v_mfma_f32_16x16x32_bf16 v[84:87], v[178:181], v[204:207], v[84:87]
	v_mfma_f32_16x16x32_bf16 v[80:83], v[188:191], v[204:207], v[80:83]
	v_mfma_f32_16x16x32_bf16 v[76:79], v[178:181], v[212:215], v[76:79]
	v_mfma_f32_16x16x32_bf16 v[72:75], v[188:191], v[212:215], v[72:75]
	v_mfma_f32_16x16x32_bf16 v[68:71], v[178:181], v[220:223], v[68:71]
	v_mfma_f32_16x16x32_bf16 v[48:51], v[188:191], v[220:223], v[48:51]
	s_setprio 0
	s_barrier
	s_add_i32 s77, s77, 2
	s_add_u32 s46, s46, 0x100
	s_addc_u32 s47, s47, 0
	s_add_u32 s75, s75, 0x100
	s_addc_u32 s76, s76, 0

.LBB0_1273:
	s_ashr_i32 s23, s22, 31
	s_lshl_b64 s[26:27], s[22:23], 20
	s_add_u32 s26, s35, s26
	s_addc_u32 s27, s36, s27
	s_and_b64 s[4:5], s[4:5], exec
	s_cselect_b32 s23, s27, s29
	s_cselect_b32 s56, s26, s28
	s_add_u32 s4, s30, 0x160080
	s_addc_u32 s5, s31, 0
	s_add_u32 s57, s28, 0x100
	s_addc_u32 s58, s29, 0
	s_mov_b32 s59, -2
	s_waitcnt lgkmcnt(0)
	ds_read_b128 v[150:153], v147
	ds_read_b128 v[154:157], v147 offset:1024
	ds_read_b128 v[158:161], v147 offset:2048
	ds_read_b128 v[162:165], v147 offset:3072
	ds_read_b128 v[166:169], v148
	ds_read_b128 v[170:173], v148 offset:1024
	ds_read_b128 v[174:177], v148 offset:2048
	ds_read_b128 v[178:181], v148 offset:3072
	s_add_u32 s28, s4, 0xffea0080
	s_addc_u32 s29, s5, -1
	s_cmp_eq_u32 s59, 28
	s_cselect_b32 s31, s25, s29
	s_cselect_b32 s30, s24, s28
	s_cselect_b32 s29, s23, s58
	s_cselect_b32 s28, s56, s57
	v_lshl_add_u64 v[216:217], s[4:5], 0, v[136:137]
	s_add_i32 m0, s39, 0xc000
	ds_read_b128 v[184:187], v149
	ds_read_b128 v[188:191], v149 offset:1024
	ds_read_b128 v[192:195], v149 offset:2048
	ds_read_b128 v[196:199], v149 offset:3072
	ds_read_b128 v[200:203], v149 offset:4096
	ds_read_b128 v[204:207], v149 offset:5120
	ds_read_b128 v[208:211], v149 offset:6144
	ds_read_b128 v[212:215], v149 offset:7168
	global_load_lds_dwordx4 v[216:217], off
	v_lshl_add_u64 v[216:217], s[4:5], 0, v[138:139]
	s_add_i32 m0, s39, 0xe000
	s_nop 0
	global_load_lds_dwordx4 v[216:217], off
	s_waitcnt vmcnt(8)
	s_waitcnt lgkmcnt(0)
	s_barrier
	s_setprio 1
	v_mfma_f32_16x16x32_bf16 v[124:127], v[150:153], v[184:187], 0
	v_mfma_f32_16x16x32_bf16 v[120:123], v[158:161], v[184:187], 0
	v_mfma_f32_16x16x32_bf16 v[116:119], v[150:153], v[192:195], 0
	v_mfma_f32_16x16x32_bf16 v[112:115], v[158:161], v[192:195], 0
	v_mfma_f32_16x16x32_bf16 v[100:103], v[150:153], v[200:203], 0
	v_mfma_f32_16x16x32_bf16 v[96:99], v[158:161], v[200:203], 0
	v_mfma_f32_16x16x32_bf16 v[84:87], v[150:153], v[208:211], 0
	v_mfma_f32_16x16x32_bf16 v[80:83], v[158:161], v[208:211], 0
	v_mfma_f32_16x16x32_bf16 v[124:127], v[154:157], v[188:191], v[124:127]
	v_mfma_f32_16x16x32_bf16 v[120:123], v[162:165], v[188:191], v[120:123]
	v_mfma_f32_16x16x32_bf16 v[116:119], v[154:157], v[196:199], v[116:119]
	v_mfma_f32_16x16x32_bf16 v[112:115], v[162:165], v[196:199], v[112:115]
	v_mfma_f32_16x16x32_bf16 v[100:103], v[154:157], v[204:207], v[100:103]
	v_mfma_f32_16x16x32_bf16 v[96:99], v[162:165], v[204:207], v[96:99]
	v_mfma_f32_16x16x32_bf16 v[84:87], v[154:157], v[212:215], v[84:87]
	v_mfma_f32_16x16x32_bf16 v[80:83], v[162:165], v[212:215], v[80:83]
	v_mfma_f32_16x16x32_bf16 v[108:111], v[166:169], v[184:187], 0
	v_mfma_f32_16x16x32_bf16 v[104:107], v[174:177], v[184:187], 0
	v_mfma_f32_16x16x32_bf16 v[92:95], v[166:169], v[192:195], 0
	v_mfma_f32_16x16x32_bf16 v[88:91], v[174:177], v[192:195], 0
	v_mfma_f32_16x16x32_bf16 v[76:79], v[166:169], v[200:203], 0
	v_mfma_f32_16x16x32_bf16 v[72:75], v[174:177], v[200:203], 0
	v_mfma_f32_16x16x32_bf16 v[68:71], v[166:169], v[208:211], 0
	v_mfma_f32_16x16x32_bf16 v[64:67], v[174:177], v[208:211], 0
	v_mfma_f32_16x16x32_bf16 v[108:111], v[170:173], v[188:191], v[108:111]
	v_mfma_f32_16x16x32_bf16 v[104:107], v[178:181], v[188:191], v[104:107]
	v_mfma_f32_16x16x32_bf16 v[92:95], v[170:173], v[196:199], v[92:95]
	v_mfma_f32_16x16x32_bf16 v[88:91], v[178:181], v[196:199], v[88:91]
	v_mfma_f32_16x16x32_bf16 v[76:79], v[170:173], v[204:207], v[76:79]
	v_mfma_f32_16x16x32_bf16 v[72:75], v[178:181], v[204:207], v[72:75]
	v_mfma_f32_16x16x32_bf16 v[68:71], v[170:173], v[212:215], v[68:71]
	v_mfma_f32_16x16x32_bf16 v[64:67], v[178:181], v[212:215], v[64:67]
	s_setprio 0
	s_barrier
	s_add_i32 s60, s47, s38
	v_lshl_add_u64 v[216:217], s[28:29], 0, v[130:131]
	s_mov_b32 m0, s60
	ds_read_b128 v[184:187], v149 offset:16384
	ds_read_b128 v[188:191], v149 offset:17408
	ds_read_b128 v[192:195], v149 offset:18432
	ds_read_b128 v[196:199], v149 offset:19456
	ds_read_b128 v[200:203], v149 offset:20480
	ds_read_b128 v[204:207], v149 offset:21504
	ds_read_b128 v[208:211], v149 offset:22528
	ds_read_b128 v[212:215], v149 offset:23552
	global_load_lds_dwordx4 v[216:217], off
	s_add_i32 m0, s60, 0x2000
	s_add_u32 s60, s28, 0x80000
	v_lshl_add_u64 v[218:219], s[28:29], 0, v[134:135]
	s_addc_u32 s61, s29, 0
	s_add_i32 s62, s48, s38
	global_load_lds_dwordx4 v[218:219], off
	v_lshl_add_u64 v[220:221], s[60:61], 0, v[130:131]
	s_mov_b32 m0, s62
	v_lshl_add_u64 v[222:223], s[30:31], 0, v[132:133]
	global_load_lds_dwordx4 v[220:221], off
	v_lshl_add_u64 v[220:221], s[60:61], 0, v[134:135]
	s_add_i32 m0, s62, 0x2000
	s_nop 0
	global_load_lds_dwordx4 v[220:221], off
	v_lshl_add_u64 v[220:221], s[30:31], 0, v[128:129]
	s_mov_b32 m0, s39
	s_nop 0
	global_load_lds_dwordx4 v[220:221], off
	s_mov_b32 m0, s40
	s_nop 0
	global_load_lds_dwordx4 v[222:223], off
	s_waitcnt vmcnt(8)
	s_waitcnt lgkmcnt(0)
	s_barrier
	s_setprio 1
	v_mfma_f32_16x16x32_bf16 v[60:63], v[150:153], v[184:187], 0
	v_mfma_f32_16x16x32_bf16 v[56:59], v[158:161], v[184:187], 0
	v_mfma_f32_16x16x32_bf16 v[52:55], v[150:153], v[192:195], 0
	v_mfma_f32_16x16x32_bf16 v[48:51], v[158:161], v[192:195], 0
	v_mfma_f32_16x16x32_bf16 v[36:39], v[150:153], v[200:203], 0
	v_mfma_f32_16x16x32_bf16 v[32:35], v[158:161], v[200:203], 0
	v_mfma_f32_16x16x32_bf16 v[20:23], v[150:153], v[208:211], 0
	v_mfma_f32_16x16x32_bf16 v[16:19], v[158:161], v[208:211], 0
	v_mfma_f32_16x16x32_bf16 v[60:63], v[154:157], v[188:191], v[60:63]
	v_mfma_f32_16x16x32_bf16 v[56:59], v[162:165], v[188:191], v[56:59]
	v_mfma_f32_16x16x32_bf16 v[52:55], v[154:157], v[196:199], v[52:55]
	v_mfma_f32_16x16x32_bf16 v[48:51], v[162:165], v[196:199], v[48:51]
	v_mfma_f32_16x16x32_bf16 v[36:39], v[154:157], v[204:207], v[36:39]
	v_mfma_f32_16x16x32_bf16 v[32:35], v[162:165], v[204:207], v[32:35]
	v_mfma_f32_16x16x32_bf16 v[20:23], v[154:157], v[212:215], v[20:23]
	v_mfma_f32_16x16x32_bf16 v[16:19], v[162:165], v[212:215], v[16:19]
	v_mfma_f32_16x16x32_bf16 v[44:47], v[166:169], v[184:187], 0
	v_mfma_f32_16x16x32_bf16 v[40:43], v[174:177], v[184:187], 0
	v_mfma_f32_16x16x32_bf16 v[28:31], v[166:169], v[192:195], 0
	v_mfma_f32_16x16x32_bf16 v[24:27], v[174:177], v[192:195], 0
	v_mfma_f32_16x16x32_bf16 v[12:15], v[166:169], v[200:203], 0
	v_mfma_f32_16x16x32_bf16 v[8:11], v[174:177], v[200:203], 0
	v_mfma_f32_16x16x32_bf16 v[4:7], v[166:169], v[208:211], 0
	v_mfma_f32_16x16x32_bf16 v[0:3], v[174:177], v[208:211], 0
	v_mfma_f32_16x16x32_bf16 v[44:47], v[170:173], v[188:191], v[44:47]
	v_mfma_f32_16x16x32_bf16 v[40:43], v[178:181], v[188:191], v[40:43]
	v_mfma_f32_16x16x32_bf16 v[28:31], v[170:173], v[196:199], v[28:31]
	v_mfma_f32_16x16x32_bf16 v[24:27], v[178:181], v[196:199], v[24:27]
	v_mfma_f32_16x16x32_bf16 v[12:15], v[170:173], v[204:207], v[12:15]
	v_mfma_f32_16x16x32_bf16 v[8:11], v[178:181], v[204:207], v[8:11]
	v_mfma_f32_16x16x32_bf16 v[4:7], v[170:173], v[212:215], v[4:7]
	v_mfma_f32_16x16x32_bf16 v[0:3], v[178:181], v[212:215], v[0:3]
	s_setprio 0
	s_barrier
	s_add_i32 s60, 0, 0x18000
	s_add_i32 s61, 0, 0x1c000
	v_add_u32_e32 v162, s60, v145
	v_add_u32_e32 v178, s61, v145
	ds_read_b128 v[150:153], v162
	ds_read_b128 v[154:157], v162 offset:1024
	ds_read_b128 v[158:161], v162 offset:2048
	ds_read_b128 v[162:165], v162 offset:3072
	ds_read_b128 v[166:169], v178
	ds_read_b128 v[170:173], v178 offset:1024
	ds_read_b128 v[174:177], v178 offset:2048
	ds_read_b128 v[178:181], v178 offset:3072
	s_add_u32 s30, s30, 0x160000
	s_addc_u32 s31, s31, 0
	s_mov_b32 m0, s41
	v_lshl_add_u64 v[224:225], s[30:31], 0, v[128:129]
	ds_read_b128 v[184:187], v149 offset:32768
	ds_read_b128 v[188:191], v149 offset:33792
	ds_read_b128 v[192:195], v149 offset:34816
	ds_read_b128 v[196:199], v149 offset:35840
	ds_read_b128 v[200:203], v149 offset:36864
	ds_read_b128 v[204:207], v149 offset:37888
	ds_read_b128 v[208:211], v149 offset:38912
	ds_read_b128 v[212:215], v149 offset:39936
	global_load_lds_dwordx4 v[224:225], off
	v_lshl_add_u64 v[224:225], s[30:31], 0, v[132:133]
	s_mov_b32 m0, s42
	s_nop 0
	global_load_lds_dwordx4 v[224:225], off
	s_waitcnt vmcnt(8)
	s_waitcnt lgkmcnt(0)
	s_barrier
	s_setprio 1
	v_mfma_f32_16x16x32_bf16 v[124:127], v[150:153], v[184:187], v[124:127]
	v_mfma_f32_16x16x32_bf16 v[120:123], v[158:161], v[184:187], v[120:123]
	v_mfma_f32_16x16x32_bf16 v[116:119], v[150:153], v[192:195], v[116:119]
	v_mfma_f32_16x16x32_bf16 v[112:115], v[158:161], v[192:195], v[112:115]
	v_mfma_f32_16x16x32_bf16 v[100:103], v[150:153], v[200:203], v[100:103]
	v_mfma_f32_16x16x32_bf16 v[96:99], v[158:161], v[200:203], v[96:99]
	v_mfma_f32_16x16x32_bf16 v[84:87], v[150:153], v[208:211], v[84:87]
	v_mfma_f32_16x16x32_bf16 v[80:83], v[158:161], v[208:211], v[80:83]
	v_mfma_f32_16x16x32_bf16 v[124:127], v[154:157], v[188:191], v[124:127]
	v_mfma_f32_16x16x32_bf16 v[120:123], v[162:165], v[188:191], v[120:123]
	v_mfma_f32_16x16x32_bf16 v[116:119], v[154:157], v[196:199], v[116:119]
	v_mfma_f32_16x16x32_bf16 v[112:115], v[162:165], v[196:199], v[112:115]
	v_mfma_f32_16x16x32_bf16 v[100:103], v[154:157], v[204:207], v[100:103]
	v_mfma_f32_16x16x32_bf16 v[96:99], v[162:165], v[204:207], v[96:99]
	v_mfma_f32_16x16x32_bf16 v[84:87], v[154:157], v[212:215], v[84:87]
	v_mfma_f32_16x16x32_bf16 v[80:83], v[162:165], v[212:215], v[80:83]
	v_mfma_f32_16x16x32_bf16 v[108:111], v[166:169], v[184:187], v[108:111]
	v_mfma_f32_16x16x32_bf16 v[104:107], v[174:177], v[184:187], v[104:107]
	v_mfma_f32_16x16x32_bf16 v[92:95], v[166:169], v[192:195], v[92:95]
	v_mfma_f32_16x16x32_bf16 v[88:91], v[174:177], v[192:195], v[88:91]
	v_mfma_f32_16x16x32_bf16 v[76:79], v[166:169], v[200:203], v[76:79]
	v_mfma_f32_16x16x32_bf16 v[72:75], v[174:177], v[200:203], v[72:75]
	v_mfma_f32_16x16x32_bf16 v[68:71], v[166:169], v[208:211], v[68:71]
	v_mfma_f32_16x16x32_bf16 v[64:67], v[174:177], v[208:211], v[64:67]
	v_mfma_f32_16x16x32_bf16 v[108:111], v[170:173], v[188:191], v[108:111]
	v_mfma_f32_16x16x32_bf16 v[104:107], v[178:181], v[188:191], v[104:107]
	v_mfma_f32_16x16x32_bf16 v[92:95], v[170:173], v[196:199], v[92:95]
	v_mfma_f32_16x16x32_bf16 v[88:91], v[178:181], v[196:199], v[88:91]
	v_mfma_f32_16x16x32_bf16 v[76:79], v[170:173], v[204:207], v[76:79]
	v_mfma_f32_16x16x32_bf16 v[72:75], v[178:181], v[204:207], v[72:75]
	v_mfma_f32_16x16x32_bf16 v[68:71], v[170:173], v[212:215], v[68:71]
	v_mfma_f32_16x16x32_bf16 v[64:67], v[178:181], v[212:215], v[64:67]
	s_setprio 0
	s_barrier
	s_add_i32 s30, s60, s38
	v_lshl_add_u64 v[216:217], v[216:217], 0, s[10:11]
	s_mov_b32 m0, s30
	ds_read_b128 v[184:187], v149 offset:49152
	ds_read_b128 v[188:191], v149 offset:50176
	ds_read_b128 v[192:195], v149 offset:51200
	ds_read_b128 v[196:199], v149 offset:52224
	ds_read_b128 v[200:203], v149 offset:53248
	ds_read_b128 v[204:207], v149 offset:54272
	ds_read_b128 v[208:211], v149 offset:55296
	ds_read_b128 v[212:215], v149 offset:56320
	global_load_lds_dwordx4 v[216:217], off
	s_add_i32 m0, s30, 0x2000
	s_add_u32 s28, s28, 0x80080
	v_lshl_add_u64 v[216:217], v[218:219], 0, s[10:11]
	s_addc_u32 s29, s29, 0
	s_add_i32 s30, s61, s38
	global_load_lds_dwordx4 v[216:217], off
	v_lshl_add_u64 v[216:217], s[28:29], 0, v[130:131]
	s_mov_b32 m0, s30
	s_nop 0
	global_load_lds_dwordx4 v[216:217], off
	v_lshl_add_u64 v[216:217], s[28:29], 0, v[134:135]
	s_add_i32 m0, s30, 0x2000
	s_nop 0
	global_load_lds_dwordx4 v[216:217], off
	v_lshl_add_u64 v[216:217], v[220:221], 0, s[10:11]
	s_mov_b32 m0, s45
	s_nop 0
	global_load_lds_dwordx4 v[216:217], off
	v_lshl_add_u64 v[216:217], v[222:223], 0, s[10:11]
	s_mov_b32 m0, s46
	s_nop 0
	global_load_lds_dwordx4 v[216:217], off
	s_waitcnt vmcnt(8)
	s_waitcnt lgkmcnt(0)
	s_barrier
	s_setprio 1
	v_mfma_f32_16x16x32_bf16 v[60:63], v[150:153], v[184:187], v[60:63]
	v_mfma_f32_16x16x32_bf16 v[56:59], v[158:161], v[184:187], v[56:59]
	v_mfma_f32_16x16x32_bf16 v[52:55], v[150:153], v[192:195], v[52:55]
	v_mfma_f32_16x16x32_bf16 v[48:51], v[158:161], v[192:195], v[48:51]
	v_mfma_f32_16x16x32_bf16 v[36:39], v[150:153], v[200:203], v[36:39]
	v_mfma_f32_16x16x32_bf16 v[32:35], v[158:161], v[200:203], v[32:35]
	v_mfma_f32_16x16x32_bf16 v[20:23], v[150:153], v[208:211], v[20:23]
	v_mfma_f32_16x16x32_bf16 v[16:19], v[158:161], v[208:211], v[16:19]
	v_mfma_f32_16x16x32_bf16 v[60:63], v[154:157], v[188:191], v[60:63]
	v_mfma_f32_16x16x32_bf16 v[56:59], v[162:165], v[188:191], v[56:59]
	v_mfma_f32_16x16x32_bf16 v[52:55], v[154:157], v[196:199], v[52:55]
	v_mfma_f32_16x16x32_bf16 v[48:51], v[162:165], v[196:199], v[48:51]
	v_mfma_f32_16x16x32_bf16 v[36:39], v[154:157], v[204:207], v[36:39]
	v_mfma_f32_16x16x32_bf16 v[32:35], v[162:165], v[204:207], v[32:35]
	v_mfma_f32_16x16x32_bf16 v[20:23], v[154:157], v[212:215], v[20:23]
	v_mfma_f32_16x16x32_bf16 v[16:19], v[162:165], v[212:215], v[16:19]
	v_mfma_f32_16x16x32_bf16 v[44:47], v[166:169], v[184:187], v[44:47]
	v_mfma_f32_16x16x32_bf16 v[40:43], v[174:177], v[184:187], v[40:43]
	v_mfma_f32_16x16x32_bf16 v[28:31], v[166:169], v[192:195], v[28:31]
	v_mfma_f32_16x16x32_bf16 v[24:27], v[174:177], v[192:195], v[24:27]
	v_mfma_f32_16x16x32_bf16 v[12:15], v[166:169], v[200:203], v[12:15]
	v_mfma_f32_16x16x32_bf16 v[8:11], v[174:177], v[200:203], v[8:11]
	v_mfma_f32_16x16x32_bf16 v[4:7], v[166:169], v[208:211], v[4:7]
	v_mfma_f32_16x16x32_bf16 v[0:3], v[174:177], v[208:211], v[0:3]
	v_mfma_f32_16x16x32_bf16 v[44:47], v[170:173], v[188:191], v[44:47]
	v_mfma_f32_16x16x32_bf16 v[40:43], v[178:181], v[188:191], v[40:43]
	v_mfma_f32_16x16x32_bf16 v[28:31], v[170:173], v[196:199], v[28:31]
	v_mfma_f32_16x16x32_bf16 v[24:27], v[178:181], v[196:199], v[24:27]
	v_mfma_f32_16x16x32_bf16 v[12:15], v[170:173], v[204:207], v[12:15]
	v_mfma_f32_16x16x32_bf16 v[8:11], v[178:181], v[204:207], v[8:11]
	v_mfma_f32_16x16x32_bf16 v[4:7], v[170:173], v[212:215], v[4:7]
	v_mfma_f32_16x16x32_bf16 v[0:3], v[178:181], v[212:215], v[0:3]
	s_setprio 0
	s_barrier
	s_add_i32 s59, s59, 2
	s_add_u32 s4, s4, 0x100
	s_addc_u32 s5, s5, 0
	s_add_u32 s57, s57, 0x100
	s_addc_u32 s58, s58, 0

.LBB0_1408:
	s_ashr_i32 s15, s14, 31
	s_lshl_b64 s[16:17], s[14:15], 19
	s_add_u32 s16, s28, s16
	s_addc_u32 s17, s29, s17
	s_and_b64 s[18:19], s[0:1], exec
	s_cselect_b32 s15, s17, s23
	s_cselect_b32 s47, s16, s22
	s_ashr_i32 s13, s12, 31
	s_lshl_b64 s[18:19], s[12:13], 19
	s_add_u32 s18, s30, s18
	s_addc_u32 s19, s31, s19
	s_and_b64 s[26:27], s[0:1], exec
	s_cselect_b32 s13, s19, s25
	s_cselect_b32 s48, s18, s24
	s_add_u32 s22, s22, 0x40080
	s_addc_u32 s23, s23, 0
	s_add_u32 s49, s24, 0x100
	s_addc_u32 s50, s25, 0
	s_mov_b32 s51, -2
	s_waitcnt lgkmcnt(0)
	ds_read_b128 v[152:155], v149
	ds_read_b128 v[156:159], v149 offset:1024
	ds_read_b128 v[160:163], v149 offset:2048
	ds_read_b128 v[164:167], v149 offset:3072
	ds_read_b128 v[168:171], v150
	ds_read_b128 v[172:175], v150 offset:1024
	ds_read_b128 v[176:179], v150 offset:2048
	ds_read_b128 v[184:187], v150 offset:3072
	s_add_u32 s24, s22, 0xfffc0080
	s_addc_u32 s25, s23, -1
	s_cmp_eq_u32 s51, 12
	s_cselect_b32 s27, s15, s25
	s_cselect_b32 s26, s47, s24
	s_cselect_b32 s25, s13, s50
	s_cselect_b32 s24, s48, s49
	v_lshl_add_u64 v[144:145], s[22:23], 0, v[136:137]
	s_add_i32 m0, s21, 0xc000
	ds_read_b128 v[188:191], v151
	ds_read_b128 v[192:195], v151 offset:1024
	ds_read_b128 v[196:199], v151 offset:2048
	ds_read_b128 v[200:203], v151 offset:3072
	ds_read_b128 v[204:207], v151 offset:4096
	ds_read_b128 v[208:211], v151 offset:5120
	ds_read_b128 v[212:215], v151 offset:6144
	ds_read_b128 v[216:219], v151 offset:7168
	global_load_lds_dwordx4 v[144:145], off
	v_lshl_add_u64 v[144:145], s[22:23], 0, v[138:139]
	s_add_i32 m0, s21, 0xe000
	s_nop 0
	global_load_lds_dwordx4 v[144:145], off
	s_waitcnt vmcnt(8)
	s_waitcnt lgkmcnt(0)
	s_barrier
	s_setprio 1
	v_mfma_f32_16x16x32_bf16 v[124:127], v[152:155], v[188:191], 0
	v_mfma_f32_16x16x32_bf16 v[120:123], v[160:163], v[188:191], 0
	v_mfma_f32_16x16x32_bf16 v[108:111], v[152:155], v[196:199], 0
	v_mfma_f32_16x16x32_bf16 v[104:107], v[160:163], v[196:199], 0
	v_mfma_f32_16x16x32_bf16 v[92:95], v[152:155], v[204:207], 0
	v_mfma_f32_16x16x32_bf16 v[88:91], v[160:163], v[204:207], 0
	v_mfma_f32_16x16x32_bf16 v[76:79], v[152:155], v[212:215], 0
	v_mfma_f32_16x16x32_bf16 v[72:75], v[160:163], v[212:215], 0
	v_mfma_f32_16x16x32_bf16 v[124:127], v[156:159], v[192:195], v[124:127]
	v_mfma_f32_16x16x32_bf16 v[120:123], v[164:167], v[192:195], v[120:123]
	v_mfma_f32_16x16x32_bf16 v[108:111], v[156:159], v[200:203], v[108:111]
	v_mfma_f32_16x16x32_bf16 v[104:107], v[164:167], v[200:203], v[104:107]
	v_mfma_f32_16x16x32_bf16 v[92:95], v[156:159], v[208:211], v[92:95]
	v_mfma_f32_16x16x32_bf16 v[88:91], v[164:167], v[208:211], v[88:91]
	v_mfma_f32_16x16x32_bf16 v[76:79], v[156:159], v[216:219], v[76:79]
	v_mfma_f32_16x16x32_bf16 v[72:75], v[164:167], v[216:219], v[72:75]
	v_mfma_f32_16x16x32_bf16 v[116:119], v[168:171], v[188:191], 0
	v_mfma_f32_16x16x32_bf16 v[112:115], v[176:179], v[188:191], 0
	v_mfma_f32_16x16x32_bf16 v[100:103], v[168:171], v[196:199], 0
	v_mfma_f32_16x16x32_bf16 v[96:99], v[176:179], v[196:199], 0
	v_mfma_f32_16x16x32_bf16 v[84:87], v[168:171], v[204:207], 0
	v_mfma_f32_16x16x32_bf16 v[80:83], v[176:179], v[204:207], 0
	v_mfma_f32_16x16x32_bf16 v[68:71], v[168:171], v[212:215], 0
	v_mfma_f32_16x16x32_bf16 v[64:67], v[176:179], v[212:215], 0
	v_mfma_f32_16x16x32_bf16 v[116:119], v[172:175], v[192:195], v[116:119]
	v_mfma_f32_16x16x32_bf16 v[112:115], v[184:187], v[192:195], v[112:115]
	v_mfma_f32_16x16x32_bf16 v[100:103], v[172:175], v[200:203], v[100:103]
	v_mfma_f32_16x16x32_bf16 v[96:99], v[184:187], v[200:203], v[96:99]
	v_mfma_f32_16x16x32_bf16 v[84:87], v[172:175], v[208:211], v[84:87]
	v_mfma_f32_16x16x32_bf16 v[80:83], v[184:187], v[208:211], v[80:83]
	v_mfma_f32_16x16x32_bf16 v[68:71], v[172:175], v[216:219], v[68:71]
	v_mfma_f32_16x16x32_bf16 v[64:67], v[184:187], v[216:219], v[64:67]
	s_setprio 0
	s_barrier
	s_add_i32 s52, s43, s34
	v_lshl_add_u64 v[144:145], s[24:25], 0, v[130:131]
	s_mov_b32 m0, s52
	ds_read_b128 v[188:191], v151 offset:16384
	ds_read_b128 v[192:195], v151 offset:17408
	ds_read_b128 v[196:199], v151 offset:18432
	ds_read_b128 v[200:203], v151 offset:19456
	ds_read_b128 v[204:207], v151 offset:20480
	ds_read_b128 v[208:211], v151 offset:21504
	ds_read_b128 v[212:215], v151 offset:22528
	ds_read_b128 v[216:219], v151 offset:23552
	global_load_lds_dwordx4 v[144:145], off
	s_add_i32 m0, s52, 0x2000
	s_add_u32 s52, s24, 0x40000
	v_lshl_add_u64 v[180:181], s[24:25], 0, v[134:135]
	s_addc_u32 s53, s25, 0
	s_add_i32 s54, s44, s34
	global_load_lds_dwordx4 v[180:181], off
	v_lshl_add_u64 v[220:221], s[52:53], 0, v[130:131]
	s_mov_b32 m0, s54
	v_lshl_add_u64 v[222:223], s[26:27], 0, v[132:133]
	global_load_lds_dwordx4 v[220:221], off
	v_lshl_add_u64 v[220:221], s[52:53], 0, v[134:135]
	s_add_i32 m0, s54, 0x2000
	s_nop 0
	global_load_lds_dwordx4 v[220:221], off
	v_lshl_add_u64 v[220:221], s[26:27], 0, v[128:129]
	s_mov_b32 m0, s21
	s_nop 0
	global_load_lds_dwordx4 v[220:221], off
	s_mov_b32 m0, s36
	s_nop 0
	global_load_lds_dwordx4 v[222:223], off
	s_waitcnt vmcnt(8)
	s_waitcnt lgkmcnt(0)
	s_barrier
	s_setprio 1
	v_mfma_f32_16x16x32_bf16 v[60:63], v[152:155], v[188:191], 0
	v_mfma_f32_16x16x32_bf16 v[56:59], v[160:163], v[188:191], 0
	v_mfma_f32_16x16x32_bf16 v[44:47], v[152:155], v[196:199], 0
	v_mfma_f32_16x16x32_bf16 v[40:43], v[160:163], v[196:199], 0
	v_mfma_f32_16x16x32_bf16 v[28:31], v[152:155], v[204:207], 0
	v_mfma_f32_16x16x32_bf16 v[24:27], v[160:163], v[204:207], 0
	v_mfma_f32_16x16x32_bf16 v[12:15], v[152:155], v[212:215], 0
	v_mfma_f32_16x16x32_bf16 v[8:11], v[160:163], v[212:215], 0
	v_mfma_f32_16x16x32_bf16 v[60:63], v[156:159], v[192:195], v[60:63]
	v_mfma_f32_16x16x32_bf16 v[56:59], v[164:167], v[192:195], v[56:59]
	v_mfma_f32_16x16x32_bf16 v[44:47], v[156:159], v[200:203], v[44:47]
	v_mfma_f32_16x16x32_bf16 v[40:43], v[164:167], v[200:203], v[40:43]
	v_mfma_f32_16x16x32_bf16 v[28:31], v[156:159], v[208:211], v[28:31]
	v_mfma_f32_16x16x32_bf16 v[24:27], v[164:167], v[208:211], v[24:27]
	v_mfma_f32_16x16x32_bf16 v[12:15], v[156:159], v[216:219], v[12:15]
	v_mfma_f32_16x16x32_bf16 v[8:11], v[164:167], v[216:219], v[8:11]
	v_mfma_f32_16x16x32_bf16 v[52:55], v[168:171], v[188:191], 0
	v_mfma_f32_16x16x32_bf16 v[48:51], v[176:179], v[188:191], 0
	v_mfma_f32_16x16x32_bf16 v[36:39], v[168:171], v[196:199], 0
	v_mfma_f32_16x16x32_bf16 v[32:35], v[176:179], v[196:199], 0
	v_mfma_f32_16x16x32_bf16 v[20:23], v[168:171], v[204:207], 0
	v_mfma_f32_16x16x32_bf16 v[16:19], v[176:179], v[204:207], 0
	v_mfma_f32_16x16x32_bf16 v[4:7], v[168:171], v[212:215], 0
	v_mfma_f32_16x16x32_bf16 v[0:3], v[176:179], v[212:215], 0
	v_mfma_f32_16x16x32_bf16 v[52:55], v[172:175], v[192:195], v[52:55]
	v_mfma_f32_16x16x32_bf16 v[48:51], v[184:187], v[192:195], v[48:51]
	v_mfma_f32_16x16x32_bf16 v[36:39], v[172:175], v[200:203], v[36:39]
	v_mfma_f32_16x16x32_bf16 v[32:35], v[184:187], v[200:203], v[32:35]
	v_mfma_f32_16x16x32_bf16 v[20:23], v[172:175], v[208:211], v[20:23]
	v_mfma_f32_16x16x32_bf16 v[16:19], v[184:187], v[208:211], v[16:19]
	v_mfma_f32_16x16x32_bf16 v[4:7], v[172:175], v[216:219], v[4:7]
	v_mfma_f32_16x16x32_bf16 v[0:3], v[184:187], v[216:219], v[0:3]
	s_setprio 0
	s_barrier
	s_add_i32 s52, 0, 0x18000
	s_add_i32 s53, 0, 0x1c000
	v_add_u32_e32 v164, s52, v147
	v_add_u32_e32 v183, s53, v147
	ds_read_b128 v[152:155], v164
	ds_read_b128 v[156:159], v164 offset:1024
	ds_read_b128 v[160:163], v164 offset:2048
	ds_read_b128 v[164:167], v164 offset:3072
	ds_read_b128 v[168:171], v183
	ds_read_b128 v[172:175], v183 offset:1024
	ds_read_b128 v[176:179], v183 offset:2048
	ds_read_b128 v[184:187], v183 offset:3072
	s_add_u32 s26, s26, 0x40000
	s_addc_u32 s27, s27, 0
	s_mov_b32 m0, s37
	v_lshl_add_u64 v[224:225], s[26:27], 0, v[128:129]
	ds_read_b128 v[188:191], v151 offset:32768
	ds_read_b128 v[192:195], v151 offset:33792
	ds_read_b128 v[196:199], v151 offset:34816
	ds_read_b128 v[200:203], v151 offset:35840
	ds_read_b128 v[204:207], v151 offset:36864
	ds_read_b128 v[208:211], v151 offset:37888
	ds_read_b128 v[212:215], v151 offset:38912
	ds_read_b128 v[216:219], v151 offset:39936
	global_load_lds_dwordx4 v[224:225], off
	v_lshl_add_u64 v[224:225], s[26:27], 0, v[132:133]
	s_mov_b32 m0, s38
	s_nop 0
	global_load_lds_dwordx4 v[224:225], off
	s_waitcnt vmcnt(8)
	s_waitcnt lgkmcnt(0)
	s_barrier
	s_setprio 1
	v_mfma_f32_16x16x32_bf16 v[124:127], v[152:155], v[188:191], v[124:127]
	v_mfma_f32_16x16x32_bf16 v[120:123], v[160:163], v[188:191], v[120:123]
	v_mfma_f32_16x16x32_bf16 v[108:111], v[152:155], v[196:199], v[108:111]
	v_mfma_f32_16x16x32_bf16 v[104:107], v[160:163], v[196:199], v[104:107]
	v_mfma_f32_16x16x32_bf16 v[92:95], v[152:155], v[204:207], v[92:95]
	v_mfma_f32_16x16x32_bf16 v[88:91], v[160:163], v[204:207], v[88:91]
	v_mfma_f32_16x16x32_bf16 v[76:79], v[152:155], v[212:215], v[76:79]
	v_mfma_f32_16x16x32_bf16 v[72:75], v[160:163], v[212:215], v[72:75]
	v_mfma_f32_16x16x32_bf16 v[124:127], v[156:159], v[192:195], v[124:127]
	v_mfma_f32_16x16x32_bf16 v[120:123], v[164:167], v[192:195], v[120:123]
	v_mfma_f32_16x16x32_bf16 v[108:111], v[156:159], v[200:203], v[108:111]
	v_mfma_f32_16x16x32_bf16 v[104:107], v[164:167], v[200:203], v[104:107]
	v_mfma_f32_16x16x32_bf16 v[92:95], v[156:159], v[208:211], v[92:95]
	v_mfma_f32_16x16x32_bf16 v[88:91], v[164:167], v[208:211], v[88:91]
	v_mfma_f32_16x16x32_bf16 v[76:79], v[156:159], v[216:219], v[76:79]
	v_mfma_f32_16x16x32_bf16 v[72:75], v[164:167], v[216:219], v[72:75]
	v_mfma_f32_16x16x32_bf16 v[116:119], v[168:171], v[188:191], v[116:119]
	v_mfma_f32_16x16x32_bf16 v[112:115], v[176:179], v[188:191], v[112:115]
	v_mfma_f32_16x16x32_bf16 v[100:103], v[168:171], v[196:199], v[100:103]
	v_mfma_f32_16x16x32_bf16 v[96:99], v[176:179], v[196:199], v[96:99]
	v_mfma_f32_16x16x32_bf16 v[84:87], v[168:171], v[204:207], v[84:87]
	v_mfma_f32_16x16x32_bf16 v[80:83], v[176:179], v[204:207], v[80:83]
	v_mfma_f32_16x16x32_bf16 v[68:71], v[168:171], v[212:215], v[68:71]
	v_mfma_f32_16x16x32_bf16 v[64:67], v[176:179], v[212:215], v[64:67]
	v_mfma_f32_16x16x32_bf16 v[116:119], v[172:175], v[192:195], v[116:119]
	v_mfma_f32_16x16x32_bf16 v[112:115], v[184:187], v[192:195], v[112:115]
	v_mfma_f32_16x16x32_bf16 v[100:103], v[172:175], v[200:203], v[100:103]
	v_mfma_f32_16x16x32_bf16 v[96:99], v[184:187], v[200:203], v[96:99]
	v_mfma_f32_16x16x32_bf16 v[84:87], v[172:175], v[208:211], v[84:87]
	v_mfma_f32_16x16x32_bf16 v[80:83], v[184:187], v[208:211], v[80:83]
	v_mfma_f32_16x16x32_bf16 v[68:71], v[172:175], v[216:219], v[68:71]
	v_mfma_f32_16x16x32_bf16 v[64:67], v[184:187], v[216:219], v[64:67]
	s_setprio 0
	s_barrier
	s_add_i32 s26, s52, s34
	v_lshl_add_u64 v[144:145], v[144:145], 0, s[8:9]
	s_mov_b32 m0, s26
	ds_read_b128 v[188:191], v151 offset:49152
	ds_read_b128 v[192:195], v151 offset:50176
	ds_read_b128 v[196:199], v151 offset:51200
	ds_read_b128 v[200:203], v151 offset:52224
	ds_read_b128 v[204:207], v151 offset:53248
	ds_read_b128 v[208:211], v151 offset:54272
	ds_read_b128 v[212:215], v151 offset:55296
	ds_read_b128 v[216:219], v151 offset:56320
	global_load_lds_dwordx4 v[144:145], off
	s_add_i32 m0, s26, 0x2000
	s_add_u32 s24, s24, 0x40080
	v_lshl_add_u64 v[144:145], v[180:181], 0, s[8:9]
	s_addc_u32 s25, s25, 0
	s_add_i32 s26, s53, s34
	global_load_lds_dwordx4 v[144:145], off
	v_lshl_add_u64 v[144:145], s[24:25], 0, v[130:131]
	s_mov_b32 m0, s26
	s_nop 0
	global_load_lds_dwordx4 v[144:145], off
	v_lshl_add_u64 v[144:145], s[24:25], 0, v[134:135]
	s_add_i32 m0, s26, 0x2000
	s_nop 0
	global_load_lds_dwordx4 v[144:145], off
	v_lshl_add_u64 v[144:145], v[220:221], 0, s[8:9]
	s_mov_b32 m0, s41
	s_nop 0
	global_load_lds_dwordx4 v[144:145], off
	v_lshl_add_u64 v[144:145], v[222:223], 0, s[8:9]
	s_mov_b32 m0, s42
	s_nop 0
	global_load_lds_dwordx4 v[144:145], off
	s_waitcnt vmcnt(8)
	s_waitcnt lgkmcnt(0)
	s_barrier
	s_setprio 1
	v_mfma_f32_16x16x32_bf16 v[60:63], v[152:155], v[188:191], v[60:63]
	v_mfma_f32_16x16x32_bf16 v[56:59], v[160:163], v[188:191], v[56:59]
	v_mfma_f32_16x16x32_bf16 v[44:47], v[152:155], v[196:199], v[44:47]
	v_mfma_f32_16x16x32_bf16 v[40:43], v[160:163], v[196:199], v[40:43]
	v_mfma_f32_16x16x32_bf16 v[28:31], v[152:155], v[204:207], v[28:31]
	v_mfma_f32_16x16x32_bf16 v[24:27], v[160:163], v[204:207], v[24:27]
	v_mfma_f32_16x16x32_bf16 v[12:15], v[152:155], v[212:215], v[12:15]
	v_mfma_f32_16x16x32_bf16 v[8:11], v[160:163], v[212:215], v[8:11]
	v_mfma_f32_16x16x32_bf16 v[60:63], v[156:159], v[192:195], v[60:63]
	v_mfma_f32_16x16x32_bf16 v[56:59], v[164:167], v[192:195], v[56:59]
	v_mfma_f32_16x16x32_bf16 v[44:47], v[156:159], v[200:203], v[44:47]
	v_mfma_f32_16x16x32_bf16 v[40:43], v[164:167], v[200:203], v[40:43]
	v_mfma_f32_16x16x32_bf16 v[28:31], v[156:159], v[208:211], v[28:31]
	v_mfma_f32_16x16x32_bf16 v[24:27], v[164:167], v[208:211], v[24:27]
	v_mfma_f32_16x16x32_bf16 v[12:15], v[156:159], v[216:219], v[12:15]
	v_mfma_f32_16x16x32_bf16 v[8:11], v[164:167], v[216:219], v[8:11]
	v_mfma_f32_16x16x32_bf16 v[52:55], v[168:171], v[188:191], v[52:55]
	v_mfma_f32_16x16x32_bf16 v[48:51], v[176:179], v[188:191], v[48:51]
	v_mfma_f32_16x16x32_bf16 v[36:39], v[168:171], v[196:199], v[36:39]
	v_mfma_f32_16x16x32_bf16 v[32:35], v[176:179], v[196:199], v[32:35]
	v_mfma_f32_16x16x32_bf16 v[20:23], v[168:171], v[204:207], v[20:23]
	v_mfma_f32_16x16x32_bf16 v[16:19], v[176:179], v[204:207], v[16:19]
	v_mfma_f32_16x16x32_bf16 v[4:7], v[168:171], v[212:215], v[4:7]
	v_mfma_f32_16x16x32_bf16 v[0:3], v[176:179], v[212:215], v[0:3]
	v_mfma_f32_16x16x32_bf16 v[52:55], v[172:175], v[192:195], v[52:55]
	v_mfma_f32_16x16x32_bf16 v[48:51], v[184:187], v[192:195], v[48:51]
	v_mfma_f32_16x16x32_bf16 v[36:39], v[172:175], v[200:203], v[36:39]
	v_mfma_f32_16x16x32_bf16 v[32:35], v[184:187], v[200:203], v[32:35]
	v_mfma_f32_16x16x32_bf16 v[20:23], v[172:175], v[208:211], v[20:23]
	v_mfma_f32_16x16x32_bf16 v[16:19], v[184:187], v[208:211], v[16:19]
	v_mfma_f32_16x16x32_bf16 v[4:7], v[172:175], v[216:219], v[4:7]
	v_mfma_f32_16x16x32_bf16 v[0:3], v[184:187], v[216:219], v[0:3]
	s_setprio 0
	s_barrier
	s_add_i32 s51, s51, 2
	s_add_u32 s22, s22, 0x100
	s_addc_u32 s23, s23, 0
	s_add_u32 s49, s49, 0x100
	s_addc_u32 s50, s50, 0

.LBB0_1487:
	s_add_u32 s24, s24, 0xb0080
	s_addc_u32 s25, s25, 0
	s_add_u32 s55, s26, 0x100
	s_addc_u32 s56, s27, 0
	s_mov_b32 s57, -2
	s_waitcnt lgkmcnt(0)
	ds_read_b128 v[150:153], v147
	ds_read_b128 v[154:157], v147 offset:1024
	ds_read_b128 v[158:161], v147 offset:2048
	ds_read_b128 v[162:165], v147 offset:3072
	ds_read_b128 v[166:169], v148
	ds_read_b128 v[170:173], v148 offset:1024
	ds_read_b128 v[174:177], v148 offset:2048
	ds_read_b128 v[178:181], v148 offset:3072
	s_add_u32 s26, s24, 0xfff50080
	s_addc_u32 s27, s25, -1
	s_cmp_eq_u32 s57, 40
	s_cselect_b32 s29, s5, s27
	s_cselect_b32 s28, s4, s26
	s_cselect_b32 s27, s23, s56
	s_cselect_b32 s26, s22, s55
	v_lshl_add_u64 v[216:217], s[24:25], 0, v[136:137]
	s_add_i32 m0, s37, 0xc000
	ds_read_b128 v[184:187], v149
	ds_read_b128 v[188:191], v149 offset:1024
	ds_read_b128 v[192:195], v149 offset:2048
	ds_read_b128 v[196:199], v149 offset:3072
	ds_read_b128 v[200:203], v149 offset:4096
	ds_read_b128 v[204:207], v149 offset:5120
	ds_read_b128 v[208:211], v149 offset:6144
	ds_read_b128 v[212:215], v149 offset:7168
	global_load_lds_dwordx4 v[216:217], off
	v_lshl_add_u64 v[216:217], s[24:25], 0, v[138:139]
	s_add_i32 m0, s37, 0xe000
	s_nop 0
	global_load_lds_dwordx4 v[216:217], off
	s_waitcnt vmcnt(8)
	s_waitcnt lgkmcnt(0)
	s_barrier
	s_setprio 1
	v_mfma_f32_16x16x32_bf16 v[124:127], v[150:153], v[184:187], 0
	v_mfma_f32_16x16x32_bf16 v[120:123], v[158:161], v[184:187], 0
	v_mfma_f32_16x16x32_bf16 v[116:119], v[150:153], v[192:195], 0
	v_mfma_f32_16x16x32_bf16 v[112:115], v[158:161], v[192:195], 0
	v_mfma_f32_16x16x32_bf16 v[100:103], v[150:153], v[200:203], 0
	v_mfma_f32_16x16x32_bf16 v[96:99], v[158:161], v[200:203], 0
	v_mfma_f32_16x16x32_bf16 v[84:87], v[150:153], v[208:211], 0
	v_mfma_f32_16x16x32_bf16 v[80:83], v[158:161], v[208:211], 0
	v_mfma_f32_16x16x32_bf16 v[124:127], v[154:157], v[188:191], v[124:127]
	v_mfma_f32_16x16x32_bf16 v[120:123], v[162:165], v[188:191], v[120:123]
	v_mfma_f32_16x16x32_bf16 v[116:119], v[154:157], v[196:199], v[116:119]
	v_mfma_f32_16x16x32_bf16 v[112:115], v[162:165], v[196:199], v[112:115]
	v_mfma_f32_16x16x32_bf16 v[100:103], v[154:157], v[204:207], v[100:103]
	v_mfma_f32_16x16x32_bf16 v[96:99], v[162:165], v[204:207], v[96:99]
	v_mfma_f32_16x16x32_bf16 v[84:87], v[154:157], v[212:215], v[84:87]
	v_mfma_f32_16x16x32_bf16 v[80:83], v[162:165], v[212:215], v[80:83]
	v_mfma_f32_16x16x32_bf16 v[108:111], v[166:169], v[184:187], 0
	v_mfma_f32_16x16x32_bf16 v[104:107], v[174:177], v[184:187], 0
	v_mfma_f32_16x16x32_bf16 v[92:95], v[166:169], v[192:195], 0
	v_mfma_f32_16x16x32_bf16 v[88:91], v[174:177], v[192:195], 0
	v_mfma_f32_16x16x32_bf16 v[76:79], v[166:169], v[200:203], 0
	v_mfma_f32_16x16x32_bf16 v[72:75], v[174:177], v[200:203], 0
	v_mfma_f32_16x16x32_bf16 v[68:71], v[166:169], v[208:211], 0
	v_mfma_f32_16x16x32_bf16 v[64:67], v[174:177], v[208:211], 0
	v_mfma_f32_16x16x32_bf16 v[108:111], v[170:173], v[188:191], v[108:111]
	v_mfma_f32_16x16x32_bf16 v[104:107], v[178:181], v[188:191], v[104:107]
	v_mfma_f32_16x16x32_bf16 v[92:95], v[170:173], v[196:199], v[92:95]
	v_mfma_f32_16x16x32_bf16 v[88:91], v[178:181], v[196:199], v[88:91]
	v_mfma_f32_16x16x32_bf16 v[76:79], v[170:173], v[204:207], v[76:79]
	v_mfma_f32_16x16x32_bf16 v[72:75], v[178:181], v[204:207], v[72:75]
	v_mfma_f32_16x16x32_bf16 v[68:71], v[170:173], v[212:215], v[68:71]
	v_mfma_f32_16x16x32_bf16 v[64:67], v[178:181], v[212:215], v[64:67]
	s_setprio 0
	s_barrier
	s_add_i32 s58, s45, s36
	v_lshl_add_u64 v[216:217], s[26:27], 0, v[130:131]
	s_mov_b32 m0, s58
	ds_read_b128 v[184:187], v149 offset:16384
	ds_read_b128 v[188:191], v149 offset:17408
	ds_read_b128 v[192:195], v149 offset:18432
	ds_read_b128 v[196:199], v149 offset:19456
	ds_read_b128 v[200:203], v149 offset:20480
	ds_read_b128 v[204:207], v149 offset:21504
	ds_read_b128 v[208:211], v149 offset:22528
	ds_read_b128 v[212:215], v149 offset:23552
	global_load_lds_dwordx4 v[216:217], off
	s_add_i32 m0, s58, 0x2000
	s_add_u32 s58, s26, 0xb0000
	v_lshl_add_u64 v[218:219], s[26:27], 0, v[134:135]
	s_addc_u32 s59, s27, 0
	s_add_i32 s60, s46, s36
	global_load_lds_dwordx4 v[218:219], off
	v_lshl_add_u64 v[220:221], s[58:59], 0, v[130:131]
	s_mov_b32 m0, s60
	v_lshl_add_u64 v[222:223], s[28:29], 0, v[132:133]
	global_load_lds_dwordx4 v[220:221], off
	v_lshl_add_u64 v[220:221], s[58:59], 0, v[134:135]
	s_add_i32 m0, s60, 0x2000
	s_nop 0
	global_load_lds_dwordx4 v[220:221], off
	v_lshl_add_u64 v[220:221], s[28:29], 0, v[128:129]
	s_mov_b32 m0, s37
	s_nop 0
	global_load_lds_dwordx4 v[220:221], off
	s_mov_b32 m0, s38
	s_nop 0
	global_load_lds_dwordx4 v[222:223], off
	s_waitcnt vmcnt(8)
	s_waitcnt lgkmcnt(0)
	s_barrier
	s_setprio 1
	v_mfma_f32_16x16x32_bf16 v[60:63], v[150:153], v[184:187], 0
	v_mfma_f32_16x16x32_bf16 v[56:59], v[158:161], v[184:187], 0
	v_mfma_f32_16x16x32_bf16 v[52:55], v[150:153], v[192:195], 0
	v_mfma_f32_16x16x32_bf16 v[48:51], v[158:161], v[192:195], 0
	v_mfma_f32_16x16x32_bf16 v[36:39], v[150:153], v[200:203], 0
	v_mfma_f32_16x16x32_bf16 v[32:35], v[158:161], v[200:203], 0
	v_mfma_f32_16x16x32_bf16 v[20:23], v[150:153], v[208:211], 0
	v_mfma_f32_16x16x32_bf16 v[16:19], v[158:161], v[208:211], 0
	v_mfma_f32_16x16x32_bf16 v[60:63], v[154:157], v[188:191], v[60:63]
	v_mfma_f32_16x16x32_bf16 v[56:59], v[162:165], v[188:191], v[56:59]
	v_mfma_f32_16x16x32_bf16 v[52:55], v[154:157], v[196:199], v[52:55]
	v_mfma_f32_16x16x32_bf16 v[48:51], v[162:165], v[196:199], v[48:51]
	v_mfma_f32_16x16x32_bf16 v[36:39], v[154:157], v[204:207], v[36:39]
	v_mfma_f32_16x16x32_bf16 v[32:35], v[162:165], v[204:207], v[32:35]
	v_mfma_f32_16x16x32_bf16 v[20:23], v[154:157], v[212:215], v[20:23]
	v_mfma_f32_16x16x32_bf16 v[16:19], v[162:165], v[212:215], v[16:19]
	v_mfma_f32_16x16x32_bf16 v[44:47], v[166:169], v[184:187], 0
	v_mfma_f32_16x16x32_bf16 v[40:43], v[174:177], v[184:187], 0
	v_mfma_f32_16x16x32_bf16 v[28:31], v[166:169], v[192:195], 0
	v_mfma_f32_16x16x32_bf16 v[24:27], v[174:177], v[192:195], 0
	v_mfma_f32_16x16x32_bf16 v[12:15], v[166:169], v[200:203], 0
	v_mfma_f32_16x16x32_bf16 v[8:11], v[174:177], v[200:203], 0
	v_mfma_f32_16x16x32_bf16 v[4:7], v[166:169], v[208:211], 0
	v_mfma_f32_16x16x32_bf16 v[0:3], v[174:177], v[208:211], 0
	v_mfma_f32_16x16x32_bf16 v[44:47], v[170:173], v[188:191], v[44:47]
	v_mfma_f32_16x16x32_bf16 v[40:43], v[178:181], v[188:191], v[40:43]
	v_mfma_f32_16x16x32_bf16 v[28:31], v[170:173], v[196:199], v[28:31]
	v_mfma_f32_16x16x32_bf16 v[24:27], v[178:181], v[196:199], v[24:27]
	v_mfma_f32_16x16x32_bf16 v[12:15], v[170:173], v[204:207], v[12:15]
	v_mfma_f32_16x16x32_bf16 v[8:11], v[178:181], v[204:207], v[8:11]
	v_mfma_f32_16x16x32_bf16 v[4:7], v[170:173], v[212:215], v[4:7]
	v_mfma_f32_16x16x32_bf16 v[0:3], v[178:181], v[212:215], v[0:3]
	s_setprio 0
	s_barrier
	s_add_i32 s58, 0, 0x18000
	s_add_i32 s59, 0, 0x1c000
	v_add_u32_e32 v162, s58, v145
	v_add_u32_e32 v178, s59, v145
	ds_read_b128 v[150:153], v162
	ds_read_b128 v[154:157], v162 offset:1024
	ds_read_b128 v[158:161], v162 offset:2048
	ds_read_b128 v[162:165], v162 offset:3072
	ds_read_b128 v[166:169], v178
	ds_read_b128 v[170:173], v178 offset:1024
	ds_read_b128 v[174:177], v178 offset:2048
	ds_read_b128 v[178:181], v178 offset:3072
	s_add_u32 s28, s28, 0xb0000
	s_addc_u32 s29, s29, 0
	s_mov_b32 m0, s39
	v_lshl_add_u64 v[224:225], s[28:29], 0, v[128:129]
	ds_read_b128 v[184:187], v149 offset:32768
	ds_read_b128 v[188:191], v149 offset:33792
	ds_read_b128 v[192:195], v149 offset:34816
	ds_read_b128 v[196:199], v149 offset:35840
	ds_read_b128 v[200:203], v149 offset:36864
	ds_read_b128 v[204:207], v149 offset:37888
	ds_read_b128 v[208:211], v149 offset:38912
	ds_read_b128 v[212:215], v149 offset:39936
	global_load_lds_dwordx4 v[224:225], off
	v_lshl_add_u64 v[224:225], s[28:29], 0, v[132:133]
	s_mov_b32 m0, s40
	s_nop 0
	global_load_lds_dwordx4 v[224:225], off
	s_waitcnt vmcnt(8)
	s_waitcnt lgkmcnt(0)
	s_barrier
	s_setprio 1
	v_mfma_f32_16x16x32_bf16 v[124:127], v[150:153], v[184:187], v[124:127]
	v_mfma_f32_16x16x32_bf16 v[120:123], v[158:161], v[184:187], v[120:123]
	v_mfma_f32_16x16x32_bf16 v[116:119], v[150:153], v[192:195], v[116:119]
	v_mfma_f32_16x16x32_bf16 v[112:115], v[158:161], v[192:195], v[112:115]
	v_mfma_f32_16x16x32_bf16 v[100:103], v[150:153], v[200:203], v[100:103]
	v_mfma_f32_16x16x32_bf16 v[96:99], v[158:161], v[200:203], v[96:99]
	v_mfma_f32_16x16x32_bf16 v[84:87], v[150:153], v[208:211], v[84:87]
	v_mfma_f32_16x16x32_bf16 v[80:83], v[158:161], v[208:211], v[80:83]
	v_mfma_f32_16x16x32_bf16 v[124:127], v[154:157], v[188:191], v[124:127]
	v_mfma_f32_16x16x32_bf16 v[120:123], v[162:165], v[188:191], v[120:123]
	v_mfma_f32_16x16x32_bf16 v[116:119], v[154:157], v[196:199], v[116:119]
	v_mfma_f32_16x16x32_bf16 v[112:115], v[162:165], v[196:199], v[112:115]
	v_mfma_f32_16x16x32_bf16 v[100:103], v[154:157], v[204:207], v[100:103]
	v_mfma_f32_16x16x32_bf16 v[96:99], v[162:165], v[204:207], v[96:99]
	v_mfma_f32_16x16x32_bf16 v[84:87], v[154:157], v[212:215], v[84:87]
	v_mfma_f32_16x16x32_bf16 v[80:83], v[162:165], v[212:215], v[80:83]
	v_mfma_f32_16x16x32_bf16 v[108:111], v[166:169], v[184:187], v[108:111]
	v_mfma_f32_16x16x32_bf16 v[104:107], v[174:177], v[184:187], v[104:107]
	v_mfma_f32_16x16x32_bf16 v[92:95], v[166:169], v[192:195], v[92:95]
	v_mfma_f32_16x16x32_bf16 v[88:91], v[174:177], v[192:195], v[88:91]
	v_mfma_f32_16x16x32_bf16 v[76:79], v[166:169], v[200:203], v[76:79]
	v_mfma_f32_16x16x32_bf16 v[72:75], v[174:177], v[200:203], v[72:75]
	v_mfma_f32_16x16x32_bf16 v[68:71], v[166:169], v[208:211], v[68:71]
	v_mfma_f32_16x16x32_bf16 v[64:67], v[174:177], v[208:211], v[64:67]
	v_mfma_f32_16x16x32_bf16 v[108:111], v[170:173], v[188:191], v[108:111]
	v_mfma_f32_16x16x32_bf16 v[104:107], v[178:181], v[188:191], v[104:107]
	v_mfma_f32_16x16x32_bf16 v[92:95], v[170:173], v[196:199], v[92:95]
	v_mfma_f32_16x16x32_bf16 v[88:91], v[178:181], v[196:199], v[88:91]
	v_mfma_f32_16x16x32_bf16 v[76:79], v[170:173], v[204:207], v[76:79]
	v_mfma_f32_16x16x32_bf16 v[72:75], v[178:181], v[204:207], v[72:75]
	v_mfma_f32_16x16x32_bf16 v[68:71], v[170:173], v[212:215], v[68:71]
	v_mfma_f32_16x16x32_bf16 v[64:67], v[178:181], v[212:215], v[64:67]
	s_setprio 0
	s_barrier
	s_add_i32 s28, s58, s36
	v_lshl_add_u64 v[216:217], v[216:217], 0, s[10:11]
	s_mov_b32 m0, s28
	ds_read_b128 v[184:187], v149 offset:49152
	ds_read_b128 v[188:191], v149 offset:50176
	ds_read_b128 v[192:195], v149 offset:51200
	ds_read_b128 v[196:199], v149 offset:52224
	ds_read_b128 v[200:203], v149 offset:53248
	ds_read_b128 v[204:207], v149 offset:54272
	ds_read_b128 v[208:211], v149 offset:55296
	ds_read_b128 v[212:215], v149 offset:56320
	global_load_lds_dwordx4 v[216:217], off
	s_add_i32 m0, s28, 0x2000
	s_add_u32 s26, s26, 0xb0080
	v_lshl_add_u64 v[216:217], v[218:219], 0, s[10:11]
	s_addc_u32 s27, s27, 0
	s_add_i32 s28, s59, s36
	global_load_lds_dwordx4 v[216:217], off
	v_lshl_add_u64 v[216:217], s[26:27], 0, v[130:131]
	s_mov_b32 m0, s28
	s_nop 0
	global_load_lds_dwordx4 v[216:217], off
	v_lshl_add_u64 v[216:217], s[26:27], 0, v[134:135]
	s_add_i32 m0, s28, 0x2000
	s_nop 0
	global_load_lds_dwordx4 v[216:217], off
	v_lshl_add_u64 v[216:217], v[220:221], 0, s[10:11]
	s_mov_b32 m0, s43
	s_nop 0
	global_load_lds_dwordx4 v[216:217], off
	v_lshl_add_u64 v[216:217], v[222:223], 0, s[10:11]
	s_mov_b32 m0, s44
	s_nop 0
	global_load_lds_dwordx4 v[216:217], off
	s_waitcnt vmcnt(8)
	s_waitcnt lgkmcnt(0)
	s_barrier
	s_setprio 1
	v_mfma_f32_16x16x32_bf16 v[60:63], v[150:153], v[184:187], v[60:63]
	v_mfma_f32_16x16x32_bf16 v[56:59], v[158:161], v[184:187], v[56:59]
	v_mfma_f32_16x16x32_bf16 v[52:55], v[150:153], v[192:195], v[52:55]
	v_mfma_f32_16x16x32_bf16 v[48:51], v[158:161], v[192:195], v[48:51]
	v_mfma_f32_16x16x32_bf16 v[36:39], v[150:153], v[200:203], v[36:39]
	v_mfma_f32_16x16x32_bf16 v[32:35], v[158:161], v[200:203], v[32:35]
	v_mfma_f32_16x16x32_bf16 v[20:23], v[150:153], v[208:211], v[20:23]
	v_mfma_f32_16x16x32_bf16 v[16:19], v[158:161], v[208:211], v[16:19]
	v_mfma_f32_16x16x32_bf16 v[60:63], v[154:157], v[188:191], v[60:63]
	v_mfma_f32_16x16x32_bf16 v[56:59], v[162:165], v[188:191], v[56:59]
	v_mfma_f32_16x16x32_bf16 v[52:55], v[154:157], v[196:199], v[52:55]
	v_mfma_f32_16x16x32_bf16 v[48:51], v[162:165], v[196:199], v[48:51]
	v_mfma_f32_16x16x32_bf16 v[36:39], v[154:157], v[204:207], v[36:39]
	v_mfma_f32_16x16x32_bf16 v[32:35], v[162:165], v[204:207], v[32:35]
	v_mfma_f32_16x16x32_bf16 v[20:23], v[154:157], v[212:215], v[20:23]
	v_mfma_f32_16x16x32_bf16 v[16:19], v[162:165], v[212:215], v[16:19]
	v_mfma_f32_16x16x32_bf16 v[44:47], v[166:169], v[184:187], v[44:47]
	v_mfma_f32_16x16x32_bf16 v[40:43], v[174:177], v[184:187], v[40:43]
	v_mfma_f32_16x16x32_bf16 v[28:31], v[166:169], v[192:195], v[28:31]
	v_mfma_f32_16x16x32_bf16 v[24:27], v[174:177], v[192:195], v[24:27]
	v_mfma_f32_16x16x32_bf16 v[12:15], v[166:169], v[200:203], v[12:15]
	v_mfma_f32_16x16x32_bf16 v[8:11], v[174:177], v[200:203], v[8:11]
	v_mfma_f32_16x16x32_bf16 v[4:7], v[166:169], v[208:211], v[4:7]
	v_mfma_f32_16x16x32_bf16 v[0:3], v[174:177], v[208:211], v[0:3]
	v_mfma_f32_16x16x32_bf16 v[44:47], v[170:173], v[188:191], v[44:47]
	v_mfma_f32_16x16x32_bf16 v[40:43], v[178:181], v[188:191], v[40:43]
	v_mfma_f32_16x16x32_bf16 v[28:31], v[170:173], v[196:199], v[28:31]
	v_mfma_f32_16x16x32_bf16 v[24:27], v[178:181], v[196:199], v[24:27]
	v_mfma_f32_16x16x32_bf16 v[12:15], v[170:173], v[204:207], v[12:15]
	v_mfma_f32_16x16x32_bf16 v[8:11], v[178:181], v[204:207], v[8:11]
	v_mfma_f32_16x16x32_bf16 v[4:7], v[170:173], v[212:215], v[4:7]
	v_mfma_f32_16x16x32_bf16 v[0:3], v[178:181], v[212:215], v[0:3]
	s_setprio 0
	s_barrier
	s_add_i32 s57, s57, 2
	s_add_u32 s24, s24, 0x100
	s_addc_u32 s25, s25, 0
	s_add_u32 s55, s55, 0x100
	s_addc_u32 s56, s56, 0
